# nt hint on the P0 weight-transpose f32 loads (weights read once), on top of nt norm0 x loads
# speedup vs baseline: 1.0188x; 1.0038x over previous
.LBB0_129:
	s_movk_i32 s6, 0x7ff
	v_cmp_lt_i32_e32 vcc, s6, v53
	s_and_saveexec_b64 s[6:7], vcc
	s_xor_b64 s[12:13], exec, s[6:7]
	s_cbranch_execz .LBB0_215
	s_movk_i32 s6, 0xc7f
	v_cmp_lt_u32_e32 vcc, s6, v53
	s_and_saveexec_b64 s[6:7], vcc
	s_xor_b64 s[6:7], exec, s[6:7]
	s_cbranch_execz .LBB0_148
	s_movk_i32 s14, 0xe7f
	v_cmp_lt_u32_e32 vcc, s14, v53
	s_and_saveexec_b64 s[14:15], vcc
	s_xor_b64 s[14:15], exec, s[14:15]
	s_cbranch_execz .LBB0_145
	s_movk_i32 s24, 0x107f
	v_cmp_lt_u32_e32 vcc, s24, v53
	s_and_saveexec_b64 s[24:25], vcc
	s_xor_b64 s[24:25], exec, s[24:25]
	s_cbranch_execz .LBB0_142
	s_movk_i32 s26, 0x10df
	v_cmp_lt_u32_e32 vcc, s26, v53
	s_and_saveexec_b64 s[26:27], vcc
	s_xor_b64 s[26:27], exec, s[26:27]
	s_cbranch_execz .LBB0_139
	s_movk_i32 s28, 0x111f
	v_cmp_lt_u32_e32 vcc, s28, v53
	s_and_saveexec_b64 s[28:29], vcc
	s_xor_b64 s[28:29], exec, s[28:29]
	s_cbranch_execz .LBB0_136
	v_add_u32_e32 v0, 0xc00, v56
	v_and_b32_e32 v78, 0xfe0, v0
	v_lshlrev_b32_e32 v0, 2, v78
	v_lshl_add_u64 v[30:31], v[2:3], 0, v[0:1]
	v_add_co_u32_e32 v32, vcc, 0x8000, v30
	s_nop 1
	v_addc_co_u32_e32 v33, vcc, 0, v31, vcc
	v_add_co_u32_e32 v60, vcc, 0x10000, v30
	s_nop 1
	v_addc_co_u32_e32 v61, vcc, 0, v31, vcc
	v_add_co_u32_e32 v62, vcc, 0x18000, v30
	s_nop 1
	v_addc_co_u32_e32 v63, vcc, 0, v31, vcc
	v_add_co_u32_e32 v64, vcc, 0x20000, v30
	s_nop 1
	v_addc_co_u32_e32 v65, vcc, 0, v31, vcc
	v_add_co_u32_e32 v66, vcc, 0x28000, v30
	s_nop 1
	v_addc_co_u32_e32 v67, vcc, 0, v31, vcc
	v_add_co_u32_e32 v68, vcc, 0x30000, v30
	s_nop 1
	v_addc_co_u32_e32 v69, vcc, 0, v31, vcc
	v_add_co_u32_e32 v70, vcc, 0x38000, v30
	s_nop 1
	v_addc_co_u32_e32 v71, vcc, 0, v31, vcc
	global_load_dword v0, v[30:31], off nt
	global_load_dword v74, v[32:33], off nt
	global_load_dword v75, v[60:61], off nt
	global_load_dword v76, v[62:63], off nt
	global_load_dword v77, v[64:65], off nt
	global_load_dword v79, v[66:67], off nt
	global_load_dword v80, v[68:69], off nt
	global_load_dword v81, v[70:71], off nt
	v_add_co_u32_e32 v32, vcc, 0x40000, v30
	s_nop 1
	v_addc_co_u32_e32 v33, vcc, 0, v31, vcc
	v_add_co_u32_e32 v60, vcc, 0x48000, v30
	s_nop 1
	v_addc_co_u32_e32 v61, vcc, 0, v31, vcc
	v_add_co_u32_e32 v62, vcc, 0x50000, v30
	s_nop 1
	v_addc_co_u32_e32 v63, vcc, 0, v31, vcc
	v_add_co_u32_e32 v64, vcc, 0x58000, v30
	s_nop 1
	v_addc_co_u32_e32 v65, vcc, 0, v31, vcc
	v_add_co_u32_e32 v66, vcc, 0x60000, v30
	s_nop 1
	v_addc_co_u32_e32 v67, vcc, 0, v31, vcc
	v_add_co_u32_e32 v68, vcc, 0x68000, v30
	s_nop 1
	v_addc_co_u32_e32 v69, vcc, 0, v31, vcc
	v_add_co_u32_e32 v70, vcc, 0x70000, v30
	s_nop 1
	v_addc_co_u32_e32 v71, vcc, 0, v31, vcc
	v_add_co_u32_e32 v72, vcc, 0x78000, v30
	s_nop 1
	v_addc_co_u32_e32 v73, vcc, 0, v31, vcc
	global_load_dword v82, v[32:33], off nt
	global_load_dword v83, v[60:61], off nt
	global_load_dword v84, v[62:63], off nt
	global_load_dword v85, v[64:65], off nt
	global_load_dword v86, v[66:67], off nt
	global_load_dword v87, v[68:69], off nt
	global_load_dword v88, v[70:71], off nt
	global_load_dword v89, v[72:73], off nt
	v_add_co_u32_e32 v32, vcc, 0x80000, v30
	s_nop 1
	v_addc_co_u32_e32 v33, vcc, 0, v31, vcc
	v_add_co_u32_e32 v60, vcc, 0x88000, v30
	s_nop 1
	v_addc_co_u32_e32 v61, vcc, 0, v31, vcc
	v_add_co_u32_e32 v62, vcc, 0x90000, v30
	s_nop 1
	v_addc_co_u32_e32 v63, vcc, 0, v31, vcc
	v_add_co_u32_e32 v64, vcc, 0x98000, v30
	s_nop 1
	v_addc_co_u32_e32 v65, vcc, 0, v31, vcc
	v_add_co_u32_e32 v66, vcc, 0xa0000, v30
	s_nop 1
	v_addc_co_u32_e32 v67, vcc, 0, v31, vcc
	v_add_co_u32_e32 v68, vcc, 0xa8000, v30
	s_nop 1
	v_addc_co_u32_e32 v69, vcc, 0, v31, vcc
	v_add_co_u32_e32 v70, vcc, 0xb0000, v30
	s_nop 1
	v_addc_co_u32_e32 v71, vcc, 0, v31, vcc
	v_add_co_u32_e32 v72, vcc, 0xb8000, v30
	s_nop 1
	v_addc_co_u32_e32 v73, vcc, 0, v31, vcc
	global_load_dword v90, v[32:33], off nt
	global_load_dword v91, v[60:61], off nt
	global_load_dword v92, v[62:63], off nt
	global_load_dword v93, v[64:65], off nt
	global_load_dword v94, v[66:67], off nt
	global_load_dword v95, v[68:69], off nt
	global_load_dword v96, v[70:71], off nt
	s_nop 0
	global_load_dword v72, v[72:73], off nt
	v_add_co_u32_e32 v32, vcc, 0xc0000, v30
	s_nop 1
	v_addc_co_u32_e32 v33, vcc, 0, v31, vcc
	v_add_co_u32_e32 v60, vcc, 0xc8000, v30
	s_nop 1
	v_addc_co_u32_e32 v61, vcc, 0, v31, vcc
	v_add_co_u32_e32 v62, vcc, 0xd0000, v30
	s_nop 1
	v_addc_co_u32_e32 v63, vcc, 0, v31, vcc
	v_add_co_u32_e32 v64, vcc, 0xd8000, v30
	s_nop 1
	v_addc_co_u32_e32 v65, vcc, 0, v31, vcc
	v_add_co_u32_e32 v66, vcc, 0xe0000, v30
	s_nop 1
	v_addc_co_u32_e32 v67, vcc, 0, v31, vcc
	v_add_co_u32_e32 v68, vcc, 0xe8000, v30
	s_nop 1
	v_addc_co_u32_e32 v69, vcc, 0, v31, vcc
	v_add_co_u32_e32 v70, vcc, 0xf0000, v30
	s_nop 1
	v_addc_co_u32_e32 v71, vcc, 0, v31, vcc
	v_add_co_u32_e32 v30, vcc, 0xf8000, v30
	s_nop 1
	v_addc_co_u32_e32 v31, vcc, 0, v31, vcc
	global_load_dword v32, v[32:33], off nt
	s_nop 0
	global_load_dword v33, v[60:61], off nt
	s_nop 0
	global_load_dword v60, v[62:63], off nt
	global_load_dword v61, v[64:65], off nt
	s_nop 0
	global_load_dword v62, v[66:67], off nt
	global_load_dword v63, v[68:69], off nt
	global_load_dword v64, v[70:71], off nt
	s_nop 0
	global_load_dword v30, v[30:31], off nt
	s_waitcnt vmcnt(30)
	ds_write2_b32 v42, v0, v74 offset1:66
	s_waitcnt vmcnt(28)
	ds_write2_b32 v42, v75, v76 offset0:132 offset1:198
	v_add_u32_e32 v0, 0x400, v42
	s_waitcnt vmcnt(26)
	ds_write2_b32 v0, v77, v79 offset0:8 offset1:74
	s_waitcnt vmcnt(24)
	ds_write2_b32 v0, v80, v81 offset0:140 offset1:206
	v_add_u32_e32 v0, 0x800, v42
	s_waitcnt vmcnt(22)
	ds_write2_b32 v0, v82, v83 offset0:16 offset1:82
	s_waitcnt vmcnt(20)
	ds_write2_b32 v0, v84, v85 offset0:148 offset1:214
	v_add_u32_e32 v0, 0xc00, v42
	s_waitcnt vmcnt(18)
	ds_write2_b32 v0, v86, v87 offset0:24 offset1:90
	s_waitcnt vmcnt(16)
	ds_write2_b32 v0, v88, v89 offset0:156 offset1:222
	v_add_u32_e32 v0, 0x1000, v42
	s_waitcnt vmcnt(14)
	ds_write2_b32 v0, v90, v91 offset0:32 offset1:98
	s_waitcnt vmcnt(12)
	ds_write2_b32 v0, v92, v93 offset0:164 offset1:230
	v_add_u32_e32 v0, 0x1400, v42
	s_waitcnt vmcnt(10)
	ds_write2_b32 v0, v94, v95 offset0:40 offset1:106
	s_waitcnt vmcnt(8)
	ds_write2_b32 v0, v96, v72 offset0:172 offset1:238
	v_add_u32_e32 v0, 0x1800, v42
	s_waitcnt vmcnt(6)
	ds_write2_b32 v0, v32, v33 offset0:48 offset1:114
	s_waitcnt vmcnt(4)
	ds_write2_b32 v0, v60, v61 offset0:180 offset1:246
	v_add_u32_e32 v0, 0x1c00, v42
	s_waitcnt vmcnt(2)
	ds_write2_b32 v0, v62, v63 offset0:56 offset1:122
	s_waitcnt vmcnt(0)
	ds_write2_b32 v0, v64, v30 offset0:188 offset1:254
	s_waitcnt lgkmcnt(0)
	ds_read2_b32 v[60:61], v44 offset0:33 offset1:41
	ds_read2_b32 v[62:63], v44 offset1:8
	ds_read2_b32 v[64:65], v44 offset0:66 offset1:74
	ds_read2_b32 v[66:67], v44 offset0:99 offset1:107
	ds_read2_b32 v[68:69], v44 offset0:132 offset1:140
	ds_read2_b32 v[70:71], v44 offset0:165 offset1:173
	ds_read2_b32 v[72:73], v44 offset0:198 offset1:206
	ds_read2_b32 v[74:75], v44 offset0:231 offset1:239
	v_or_b32_e32 v0, v78, v43
	v_lshlrev_b32_e32 v0, 7, v0
	s_waitcnt lgkmcnt(6)
	v_cvt_pk_bf16_f32 v30, v62, v60
	s_waitcnt lgkmcnt(4)
	v_cvt_pk_bf16_f32 v31, v64, v66
	s_waitcnt lgkmcnt(2)
	v_cvt_pk_bf16_f32 v32, v68, v70
	s_waitcnt lgkmcnt(0)
	v_cvt_pk_bf16_f32 v33, v72, v74
	v_lshl_add_u64 v[76:77], v[18:19], 0, v[0:1]
	global_store_dwordx4 v[76:77], v[30:33], off
	v_or_b32_e32 v0, v78, v45
	v_lshlrev_b32_e32 v0, 7, v0
	v_cvt_pk_bf16_f32 v30, v63, v61
	v_cvt_pk_bf16_f32 v31, v65, v67
	v_cvt_pk_bf16_f32 v32, v69, v71
	v_cvt_pk_bf16_f32 v33, v73, v75
	ds_read2_b32 v[62:63], v44 offset0:49 offset1:57
	ds_read2_b32 v[64:65], v44 offset0:16 offset1:24
	ds_read2_b32 v[66:67], v44 offset0:82 offset1:90
	ds_read2_b32 v[68:69], v44 offset0:115 offset1:123
	ds_read2_b32 v[70:71], v44 offset0:148 offset1:156
	ds_read2_b32 v[72:73], v44 offset0:181 offset1:189
	ds_read2_b32 v[74:75], v44 offset0:214 offset1:222
	ds_read2_b32 v[76:77], v44 offset0:247 offset1:255
	v_lshl_add_u64 v[60:61], v[18:19], 0, v[0:1]
	v_or_b32_e32 v0, v78, v46
	v_lshlrev_b32_e32 v0, 7, v0
	global_store_dwordx4 v[60:61], v[30:33], off
	v_lshl_add_u64 v[60:61], v[18:19], 0, v[0:1]
	v_or_b32_e32 v0, v78, v47
	s_waitcnt lgkmcnt(6)
	v_cvt_pk_bf16_f32 v30, v64, v62
	s_waitcnt lgkmcnt(4)
	v_cvt_pk_bf16_f32 v31, v66, v68
	s_waitcnt lgkmcnt(2)
	v_cvt_pk_bf16_f32 v32, v70, v72
	s_waitcnt lgkmcnt(0)
	v_cvt_pk_bf16_f32 v33, v74, v76
	v_lshlrev_b32_e32 v0, 7, v0
	global_store_dwordx4 v[60:61], v[30:33], off
	v_lshl_add_u64 v[60:61], v[18:19], 0, v[0:1]
	s_nop 0
	v_cvt_pk_bf16_f32 v30, v65, v63
	v_cvt_pk_bf16_f32 v31, v67, v69
	v_cvt_pk_bf16_f32 v32, v71, v73
	v_cvt_pk_bf16_f32 v33, v75, v77
	global_store_dwordx4 v[60:61], v[30:33], off
	s_waitcnt lgkmcnt(0)
.LBB0_136:
	s_andn2_saveexec_b64 s[28:29], s[28:29]
	s_cbranch_execz .LBB0_138
	v_add_u32_e32 v0, 0xffffef20, v53
	v_add_u32_e32 v30, 0xffffef00, v53
	v_cmp_gt_u32_e32 vcc, 32, v0
	s_movk_i32 s97, 0x2000
	s_nop 0
	v_cndmask_b32_e32 v30, v30, v0, vcc
	v_cmp_lt_u32_e32 vcc, 31, v0
	v_lshlrev_b32_e32 v30, 5, v30
	v_ashrrev_i32_e32 v31, 31, v30
	v_cndmask_b32_e64 v76, 0, 64, vcc
	v_or_b32_e32 v0, v76, v41
	v_lshl_add_u64 v[32:33], v[30:31], 2, v[4:5]
	v_lshlrev_b32_e32 v0, 12, v0
	v_lshl_add_u64 v[32:33], v[32:33], 0, v[0:1]
	v_add_co_u32_e32 v60, vcc, s97, v32
	s_mov_b32 s97, 0xe000
	s_nop 0
	v_addc_co_u32_e32 v61, vcc, 0, v33, vcc
	v_add_co_u32_e32 v62, vcc, s43, v32
	s_nop 1
	v_addc_co_u32_e32 v63, vcc, 0, v33, vcc
	v_add_co_u32_e32 v64, vcc, s44, v32
	s_nop 1
	v_addc_co_u32_e32 v65, vcc, 0, v33, vcc
	v_add_co_u32_e32 v66, vcc, s3, v32
	s_nop 1
	v_addc_co_u32_e32 v67, vcc, 0, v33, vcc
	v_add_co_u32_e32 v68, vcc, s45, v32
	s_nop 1
	v_addc_co_u32_e32 v69, vcc, 0, v33, vcc
	v_add_co_u32_e32 v70, vcc, s46, v32
	s_nop 1
	v_addc_co_u32_e32 v71, vcc, 0, v33, vcc
	v_add_co_u32_e32 v72, vcc, s97, v32
	s_mov_b32 s97, 0x14000
	s_nop 0
	v_addc_co_u32_e32 v73, vcc, 0, v33, vcc
	global_load_dword v0, v[32:33], off nt
	global_load_dword v31, v[60:61], off nt
	global_load_dword v77, v[62:63], off nt
	global_load_dword v78, v[64:65], off nt
	global_load_dword v79, v[66:67], off nt
	global_load_dword v80, v[68:69], off nt
	global_load_dword v81, v[70:71], off nt
	global_load_dword v82, v[72:73], off nt
	v_add_co_u32_e32 v60, vcc, s30, v32
	s_nop 1
	v_addc_co_u32_e32 v61, vcc, 0, v33, vcc
	v_add_co_u32_e32 v62, vcc, s47, v32
	s_nop 1
	v_addc_co_u32_e32 v63, vcc, 0, v33, vcc
	v_add_co_u32_e32 v64, vcc, s97, v32
	s_mov_b32 s97, 0x1a000
	s_nop 0
	v_addc_co_u32_e32 v65, vcc, 0, v33, vcc
	v_add_co_u32_e32 v66, vcc, s48, v32
	s_nop 1
	v_addc_co_u32_e32 v67, vcc, 0, v33, vcc
	v_add_co_u32_e32 v68, vcc, s31, v32
	s_nop 1
	v_addc_co_u32_e32 v69, vcc, 0, v33, vcc
	v_add_co_u32_e32 v70, vcc, s97, v32
	s_mov_b32 s97, 0x26000
	s_nop 0
	v_addc_co_u32_e32 v71, vcc, 0, v33, vcc
	v_add_co_u32_e32 v72, vcc, s49, v32
	s_nop 1
	v_addc_co_u32_e32 v73, vcc, 0, v33, vcc
	v_add_co_u32_e32 v74, vcc, s54, v32
	s_nop 1
	v_addc_co_u32_e32 v75, vcc, 0, v33, vcc
	global_load_dword v83, v[60:61], off nt
	global_load_dword v84, v[62:63], off nt
	global_load_dword v85, v[64:65], off nt
	global_load_dword v86, v[66:67], off nt
	global_load_dword v87, v[68:69], off nt
	global_load_dword v88, v[70:71], off nt
	global_load_dword v89, v[72:73], off nt
	global_load_dword v90, v[74:75], off nt
	v_add_co_u32_e32 v60, vcc, s33, v32
	s_nop 1
	v_addc_co_u32_e32 v61, vcc, 0, v33, vcc
	v_add_co_u32_e32 v62, vcc, s55, v32
	s_nop 1
	v_addc_co_u32_e32 v63, vcc, 0, v33, vcc
	v_add_co_u32_e32 v64, vcc, s58, v32
	s_nop 1
	v_addc_co_u32_e32 v65, vcc, 0, v33, vcc
	v_add_co_u32_e32 v66, vcc, s97, v32
	s_mov_b32 s97, 0x2c000
	s_nop 0
	v_addc_co_u32_e32 v67, vcc, 0, v33, vcc
	v_add_co_u32_e32 v68, vcc, s40, v32
	s_nop 1
	v_addc_co_u32_e32 v69, vcc, 0, v33, vcc
	v_add_co_u32_e32 v70, vcc, s59, v32
	s_nop 1
	v_addc_co_u32_e32 v71, vcc, 0, v33, vcc
	v_add_co_u32_e32 v72, vcc, s97, v32
	s_mov_b32 s97, 0x32000
	s_nop 0
	v_addc_co_u32_e32 v73, vcc, 0, v33, vcc
	v_add_co_u32_e32 v74, vcc, s60, v32
	s_nop 1
	v_addc_co_u32_e32 v75, vcc, 0, v33, vcc
	global_load_dword v91, v[60:61], off nt
	global_load_dword v92, v[62:63], off nt
	global_load_dword v93, v[64:65], off nt
	global_load_dword v94, v[66:67], off nt
	global_load_dword v95, v[68:69], off nt
	global_load_dword v96, v[70:71], off nt
	global_load_dword v97, v[72:73], off nt
	s_nop 0
	global_load_dword v74, v[74:75], off nt
	v_add_co_u32_e32 v60, vcc, s41, v32
	s_nop 1
	v_addc_co_u32_e32 v61, vcc, 0, v33, vcc
	v_add_co_u32_e32 v62, vcc, s97, v32
	s_nop 1
	v_addc_co_u32_e32 v63, vcc, 0, v33, vcc
	v_add_co_u32_e32 v64, vcc, s61, v32
	s_nop 1
	v_addc_co_u32_e32 v65, vcc, 0, v33, vcc
	v_add_co_u32_e32 v66, vcc, s62, v32
	s_nop 1
	v_addc_co_u32_e32 v67, vcc, 0, v33, vcc
	v_add_co_u32_e32 v68, vcc, s42, v32
	s_nop 1
	v_addc_co_u32_e32 v69, vcc, 0, v33, vcc
	v_add_co_u32_e32 v70, vcc, s63, v32
	s_nop 1
	v_addc_co_u32_e32 v71, vcc, 0, v33, vcc
	v_add_co_u32_e32 v72, vcc, s66, v32
	s_nop 1
	v_addc_co_u32_e32 v73, vcc, 0, v33, vcc
	v_add_co_u32_e32 v32, vcc, s67, v32
	s_nop 1
	v_addc_co_u32_e32 v33, vcc, 0, v33, vcc
	global_load_dword v60, v[60:61], off nt
	s_nop 0
	global_load_dword v61, v[62:63], off nt
	s_nop 0
	global_load_dword v62, v[64:65], off nt
	global_load_dword v63, v[66:67], off nt
	s_nop 0
	global_load_dword v64, v[68:69], off nt
	global_load_dword v65, v[70:71], off nt
	global_load_dword v66, v[72:73], off nt
	s_nop 0
	global_load_dword v32, v[32:33], off nt
	s_waitcnt vmcnt(30)
	ds_write2_b32 v42, v0, v31 offset1:66
	s_waitcnt vmcnt(28)
	ds_write2_b32 v42, v77, v78 offset0:132 offset1:198
	v_add_u32_e32 v0, 0x400, v42
	s_waitcnt vmcnt(26)
	ds_write2_b32 v0, v79, v80 offset0:8 offset1:74
	s_waitcnt vmcnt(24)
	ds_write2_b32 v0, v81, v82 offset0:140 offset1:206
	v_add_u32_e32 v0, 0x800, v42
	s_waitcnt vmcnt(22)
	ds_write2_b32 v0, v83, v84 offset0:16 offset1:82
	s_waitcnt vmcnt(20)
	ds_write2_b32 v0, v85, v86 offset0:148 offset1:214
	v_add_u32_e32 v0, 0xc00, v42
	s_waitcnt vmcnt(18)
	ds_write2_b32 v0, v87, v88 offset0:24 offset1:90
	s_waitcnt vmcnt(16)
	ds_write2_b32 v0, v89, v90 offset0:156 offset1:222
	v_add_u32_e32 v0, 0x1000, v42
	s_waitcnt vmcnt(14)
	ds_write2_b32 v0, v91, v92 offset0:32 offset1:98
	s_waitcnt vmcnt(12)
	ds_write2_b32 v0, v93, v94 offset0:164 offset1:230
	v_add_u32_e32 v0, 0x1400, v42
	s_waitcnt vmcnt(10)
	ds_write2_b32 v0, v95, v96 offset0:40 offset1:106
	s_waitcnt vmcnt(8)
	ds_write2_b32 v0, v97, v74 offset0:172 offset1:238
	v_add_u32_e32 v0, 0x1800, v42
	s_waitcnt vmcnt(6)
	ds_write2_b32 v0, v60, v61 offset0:48 offset1:114
	s_waitcnt vmcnt(4)
	ds_write2_b32 v0, v62, v63 offset0:180 offset1:246
	v_add_u32_e32 v0, 0x1c00, v42
	s_waitcnt vmcnt(2)
	ds_write2_b32 v0, v64, v65 offset0:56 offset1:122
	s_waitcnt vmcnt(0)
	ds_write2_b32 v0, v66, v32 offset0:188 offset1:254
	s_waitcnt lgkmcnt(0)
	v_lshlrev_b32_e32 v0, 1, v76
	ds_read2_b32 v[32:33], v44 offset0:33 offset1:41
	ds_read2_b32 v[64:65], v44 offset1:8
	ds_read2_b32 v[66:67], v44 offset0:66 offset1:74
	ds_read2_b32 v[68:69], v44 offset0:99 offset1:107
	ds_read2_b32 v[70:71], v44 offset0:132 offset1:140
	ds_read2_b32 v[72:73], v44 offset0:165 offset1:173
	ds_read2_b32 v[74:75], v44 offset0:198 offset1:206
	ds_read2_b32 v[76:77], v44 offset0:231 offset1:239
	v_or_b32_e32 v80, v30, v43
	v_ashrrev_i32_e32 v81, 31, v80
	v_lshl_add_u64 v[78:79], v[20:21], 0, v[0:1]
	v_lshlrev_b64 v[80:81], 8, v[80:81]
	s_waitcnt lgkmcnt(6)
	v_cvt_pk_bf16_f32 v60, v64, v32
	s_waitcnt lgkmcnt(4)
	v_cvt_pk_bf16_f32 v61, v66, v68
	s_waitcnt lgkmcnt(2)
	v_cvt_pk_bf16_f32 v62, v70, v72
	s_waitcnt lgkmcnt(0)
	v_cvt_pk_bf16_f32 v63, v74, v76
	v_lshl_add_u64 v[80:81], v[78:79], 0, v[80:81]
	v_or_b32_e32 v32, v30, v45
	global_store_dwordx4 v[80:81], v[60:63], off
	s_nop 1
	v_cvt_pk_bf16_f32 v60, v65, v33
	v_ashrrev_i32_e32 v33, 31, v32
	v_cvt_pk_bf16_f32 v61, v67, v69
	v_cvt_pk_bf16_f32 v62, v71, v73
	v_cvt_pk_bf16_f32 v63, v75, v77
	v_lshlrev_b64 v[32:33], 8, v[32:33]
	ds_read2_b32 v[64:65], v44 offset0:49 offset1:57
	ds_read2_b32 v[66:67], v44 offset0:16 offset1:24
	ds_read2_b32 v[68:69], v44 offset0:82 offset1:90
	ds_read2_b32 v[70:71], v44 offset0:115 offset1:123
	ds_read2_b32 v[72:73], v44 offset0:148 offset1:156
	ds_read2_b32 v[74:75], v44 offset0:181 offset1:189
	ds_read2_b32 v[76:77], v44 offset0:214 offset1:222
	ds_read2_b32 v[80:81], v44 offset0:247 offset1:255
	v_lshl_add_u64 v[32:33], v[78:79], 0, v[32:33]
	global_store_dwordx4 v[32:33], v[60:63], off
	v_or_b32_e32 v32, v30, v46
	v_ashrrev_i32_e32 v33, 31, v32
	v_or_b32_e32 v30, v30, v47
	v_lshlrev_b64 v[32:33], 8, v[32:33]
	v_ashrrev_i32_e32 v31, 31, v30
	s_waitcnt lgkmcnt(6)
	v_cvt_pk_bf16_f32 v60, v66, v64
	s_waitcnt lgkmcnt(4)
	v_cvt_pk_bf16_f32 v61, v68, v70
	s_waitcnt lgkmcnt(2)
	v_cvt_pk_bf16_f32 v62, v72, v74
	s_waitcnt lgkmcnt(0)
	v_cvt_pk_bf16_f32 v63, v76, v80
	v_lshl_add_u64 v[32:33], v[78:79], 0, v[32:33]
	v_lshlrev_b64 v[30:31], 8, v[30:31]
	global_store_dwordx4 v[32:33], v[60:63], off
	v_lshl_add_u64 v[30:31], v[78:79], 0, v[30:31]
	s_nop 0
	v_cvt_pk_bf16_f32 v60, v67, v65
	v_cvt_pk_bf16_f32 v61, v69, v71
	v_cvt_pk_bf16_f32 v62, v73, v75
	v_cvt_pk_bf16_f32 v63, v77, v81
	global_store_dwordx4 v[30:31], v[60:63], off
	s_waitcnt lgkmcnt(0)

.LBB0_139:
	s_andn2_saveexec_b64 s[26:27], s[26:27]
	s_cbranch_execz .LBB0_141
	v_bitop3_b16 v30, v53, s68, v49 bitop3:0x48
	v_mul_lo_u16_e32 v30, 0xab, v30
	v_lshrrev_b16_e32 v74, 12, v30
	v_xor_b32_e32 v0, 0xffffff80, v53
	v_mul_lo_u16_e32 v30, 24, v74
	v_sub_u16_e32 v75, v0, v30
	v_lshl_or_b32 v32, v74, 6, v41
	v_lshlrev_b32_sdwa v0, v51, v75 dst_sel:DWORD dst_unused:UNUSED_PAD src0_sel:DWORD src1_sel:BYTE_0
	v_lshl_add_u64 v[30:31], v[6:7], 0, v[0:1]
	v_mul_u32_u24_e32 v0, 0x300, v32
	v_lshlrev_b32_e32 v0, 2, v0
	v_lshl_add_u64 v[30:31], v[30:31], 0, v[0:1]
	v_add_co_u32_e32 v32, vcc, s69, v30
	v_lshlrev_b32_sdwa v98, v50, v75 dst_sel:DWORD dst_unused:UNUSED_PAD src0_sel:DWORD src1_sel:BYTE_0
	s_nop 0
	v_addc_co_u32_e32 v33, vcc, 0, v31, vcc
	v_add_co_u32_e32 v60, vcc, s72, v30
	s_nop 1
	v_addc_co_u32_e32 v61, vcc, 0, v31, vcc
	v_add_co_u32_e32 v62, vcc, s43, v30
	s_nop 1
	v_addc_co_u32_e32 v63, vcc, 0, v31, vcc
	v_add_co_u32_e32 v64, vcc, s44, v30
	s_nop 1
	v_addc_co_u32_e32 v65, vcc, 0, v31, vcc
	v_add_co_u32_e32 v66, vcc, s73, v30
	s_nop 1
	v_addc_co_u32_e32 v67, vcc, 0, v31, vcc
	v_add_co_u32_e32 v68, vcc, s82, v30
	s_nop 1
	v_addc_co_u32_e32 v69, vcc, 0, v31, vcc
	v_add_co_u32_e32 v70, vcc, s45, v30
	s_nop 1
	v_addc_co_u32_e32 v71, vcc, 0, v31, vcc
	global_load_dword v0, v[30:31], off nt
	global_load_dword v76, v[32:33], off offset:2048 nt
	global_load_dword v77, v[60:61], off nt
	global_load_dword v78, v[62:63], off offset:2048 nt
	global_load_dword v79, v[64:65], off nt
	global_load_dword v80, v[66:67], off offset:2048 nt
	global_load_dword v81, v[68:69], off nt
	global_load_dword v82, v[70:71], off offset:2048 nt
	v_add_co_u32_e32 v32, vcc, s46, v30
	s_nop 1
	v_addc_co_u32_e32 v33, vcc, 0, v31, vcc
	v_add_co_u32_e32 v60, vcc, s83, v30
	s_nop 1
	v_addc_co_u32_e32 v61, vcc, 0, v31, vcc
	v_add_co_u32_e32 v62, vcc, s84, v30
	s_nop 1
	v_addc_co_u32_e32 v63, vcc, 0, v31, vcc
	v_add_co_u32_e32 v64, vcc, s30, v30
	s_nop 1
	v_addc_co_u32_e32 v65, vcc, 0, v31, vcc
	v_add_co_u32_e32 v66, vcc, s47, v30
	s_nop 1
	v_addc_co_u32_e32 v67, vcc, 0, v31, vcc
	v_add_co_u32_e32 v68, vcc, s85, v30
	s_nop 1
	v_addc_co_u32_e32 v69, vcc, 0, v31, vcc
	v_add_co_u32_e32 v70, vcc, s86, v30
	s_nop 1
	v_addc_co_u32_e32 v71, vcc, 0, v31, vcc
	v_add_co_u32_e32 v72, vcc, s48, v30
	s_nop 1
	v_addc_co_u32_e32 v73, vcc, 0, v31, vcc
	global_load_dword v83, v[32:33], off nt
	global_load_dword v84, v[60:61], off offset:2048 nt
	global_load_dword v85, v[62:63], off nt
	global_load_dword v86, v[64:65], off offset:2048 nt
	global_load_dword v87, v[66:67], off nt
	global_load_dword v88, v[68:69], off offset:2048 nt
	global_load_dword v89, v[70:71], off nt
	global_load_dword v90, v[72:73], off offset:2048 nt
	v_add_co_u32_e32 v32, vcc, s31, v30
	s_nop 1
	v_addc_co_u32_e32 v33, vcc, 0, v31, vcc
	v_add_co_u32_e32 v60, vcc, s87, v30
	s_nop 1
	v_addc_co_u32_e32 v61, vcc, 0, v31, vcc
	v_add_co_u32_e32 v62, vcc, s88, v30
	s_nop 1
	v_addc_co_u32_e32 v63, vcc, 0, v31, vcc
	v_add_co_u32_e32 v64, vcc, s49, v30
	s_nop 1
	v_addc_co_u32_e32 v65, vcc, 0, v31, vcc
	v_add_co_u32_e32 v66, vcc, s54, v30
	s_nop 1
	v_addc_co_u32_e32 v67, vcc, 0, v31, vcc
	v_add_co_u32_e32 v68, vcc, s89, v30
	s_nop 1
	v_addc_co_u32_e32 v69, vcc, 0, v31, vcc
	v_add_co_u32_e32 v70, vcc, s90, v30
	s_nop 1
	v_addc_co_u32_e32 v71, vcc, 0, v31, vcc
	v_add_co_u32_e32 v72, vcc, s55, v30
	s_nop 1
	v_addc_co_u32_e32 v73, vcc, 0, v31, vcc
	global_load_dword v91, v[32:33], off nt
	global_load_dword v92, v[60:61], off offset:2048 nt
	global_load_dword v93, v[62:63], off nt
	global_load_dword v94, v[64:65], off offset:2048 nt
	global_load_dword v95, v[66:67], off nt
	global_load_dword v96, v[68:69], off offset:2048 nt
	global_load_dword v97, v[70:71], off nt
	s_nop 0
	global_load_dword v72, v[72:73], off offset:2048 nt
	v_add_co_u32_e32 v32, vcc, s58, v30
	s_nop 1
	v_addc_co_u32_e32 v33, vcc, 0, v31, vcc
	v_add_co_u32_e32 v60, vcc, s91, v30
	s_nop 1
	v_addc_co_u32_e32 v61, vcc, 0, v31, vcc
	v_add_co_u32_e32 v62, vcc, s92, v30
	s_nop 1
	v_addc_co_u32_e32 v63, vcc, 0, v31, vcc
	v_add_co_u32_e32 v64, vcc, s40, v30
	s_nop 1
	v_addc_co_u32_e32 v65, vcc, 0, v31, vcc
	v_add_co_u32_e32 v66, vcc, s59, v30
	s_nop 1
	v_addc_co_u32_e32 v67, vcc, 0, v31, vcc
	v_add_co_u32_e32 v68, vcc, s93, v30
	s_nop 1
	v_addc_co_u32_e32 v69, vcc, 0, v31, vcc
	v_add_co_u32_e32 v70, vcc, s94, v30
	s_nop 1
	v_addc_co_u32_e32 v71, vcc, 0, v31, vcc
	v_add_co_u32_e32 v30, vcc, s60, v30
	s_nop 1
	v_addc_co_u32_e32 v31, vcc, 0, v31, vcc
	global_load_dword v32, v[32:33], off nt
	s_nop 0
	global_load_dword v33, v[60:61], off offset:2048 nt
	s_nop 0
	global_load_dword v60, v[62:63], off nt
	global_load_dword v61, v[64:65], off offset:2048 nt
	s_nop 0
	global_load_dword v62, v[66:67], off nt
	global_load_dword v63, v[68:69], off offset:2048 nt
	global_load_dword v64, v[70:71], off nt
	s_nop 0
	global_load_dword v30, v[30:31], off offset:2048 nt
	s_waitcnt vmcnt(30)
	ds_write2_b32 v42, v0, v76 offset1:66
	s_waitcnt vmcnt(28)
	ds_write2_b32 v42, v77, v78 offset0:132 offset1:198
	v_add_u32_e32 v0, 0x400, v42
	s_waitcnt vmcnt(26)
	ds_write2_b32 v0, v79, v80 offset0:8 offset1:74
	s_waitcnt vmcnt(24)
	ds_write2_b32 v0, v81, v82 offset0:140 offset1:206
	v_add_u32_e32 v0, 0x800, v42
	s_waitcnt vmcnt(22)
	ds_write2_b32 v0, v83, v84 offset0:16 offset1:82
	s_waitcnt vmcnt(20)
	ds_write2_b32 v0, v85, v86 offset0:148 offset1:214
	v_add_u32_e32 v0, 0xc00, v42
	s_waitcnt vmcnt(18)
	ds_write2_b32 v0, v87, v88 offset0:24 offset1:90
	s_waitcnt vmcnt(16)
	ds_write2_b32 v0, v89, v90 offset0:156 offset1:222
	v_add_u32_e32 v0, 0x1000, v42
	s_waitcnt vmcnt(14)
	ds_write2_b32 v0, v91, v92 offset0:32 offset1:98
	s_waitcnt vmcnt(12)
	ds_write2_b32 v0, v93, v94 offset0:164 offset1:230
	v_add_u32_e32 v0, 0x1400, v42
	s_waitcnt vmcnt(10)
	ds_write2_b32 v0, v95, v96 offset0:40 offset1:106
	s_waitcnt vmcnt(8)
	ds_write2_b32 v0, v97, v72 offset0:172 offset1:238
	v_add_u32_e32 v0, 0x1800, v42
	s_waitcnt vmcnt(6)
	ds_write2_b32 v0, v32, v33 offset0:48 offset1:114
	s_waitcnt vmcnt(4)
	ds_write2_b32 v0, v60, v61 offset0:180 offset1:246
	v_add_u32_e32 v0, 0x1c00, v42
	s_waitcnt vmcnt(2)
	ds_write2_b32 v0, v62, v63 offset0:56 offset1:122
	s_waitcnt vmcnt(0)
	ds_write2_b32 v0, v64, v30 offset0:188 offset1:254
	s_waitcnt lgkmcnt(0)
	v_lshlrev_b32_e32 v0, 7, v74
	ds_read2_b32 v[60:61], v44 offset0:33 offset1:41
	ds_read2_b32 v[62:63], v44 offset1:8
	ds_read2_b32 v[64:65], v44 offset0:66 offset1:74
	ds_read2_b32 v[66:67], v44 offset0:99 offset1:107
	ds_read2_b32 v[68:69], v44 offset0:132 offset1:140
	ds_read2_b32 v[70:71], v44 offset0:165 offset1:173
	ds_read2_b32 v[72:73], v44 offset0:198 offset1:206
	ds_read2_b32 v[74:75], v44 offset0:231 offset1:239
	v_lshl_add_u64 v[76:77], v[22:23], 0, v[0:1]
	v_or_b32_e32 v0, v98, v43
	v_lshlrev_b32_e32 v0, 9, v0
	s_waitcnt lgkmcnt(6)
	v_cvt_pk_bf16_f32 v30, v62, v60
	s_waitcnt lgkmcnt(4)
	v_cvt_pk_bf16_f32 v31, v64, v66
	s_waitcnt lgkmcnt(2)
	v_cvt_pk_bf16_f32 v32, v68, v70
	s_waitcnt lgkmcnt(0)
	v_cvt_pk_bf16_f32 v33, v72, v74
	v_lshl_add_u64 v[78:79], v[76:77], 0, v[0:1]
	global_store_dwordx4 v[78:79], v[30:33], off
	v_or_b32_e32 v0, v98, v45
	v_lshlrev_b32_e32 v0, 9, v0
	v_cvt_pk_bf16_f32 v30, v63, v61
	v_cvt_pk_bf16_f32 v31, v65, v67
	v_cvt_pk_bf16_f32 v32, v69, v71
	v_cvt_pk_bf16_f32 v33, v73, v75
	ds_read2_b32 v[62:63], v44 offset0:49 offset1:57
	ds_read2_b32 v[64:65], v44 offset0:16 offset1:24
	ds_read2_b32 v[66:67], v44 offset0:82 offset1:90
	ds_read2_b32 v[68:69], v44 offset0:115 offset1:123
	ds_read2_b32 v[70:71], v44 offset0:148 offset1:156
	ds_read2_b32 v[72:73], v44 offset0:181 offset1:189
	ds_read2_b32 v[74:75], v44 offset0:214 offset1:222
	ds_read2_b32 v[78:79], v44 offset0:247 offset1:255
	v_lshl_add_u64 v[60:61], v[76:77], 0, v[0:1]
	v_or_b32_e32 v0, v98, v46
	v_lshlrev_b32_e32 v0, 9, v0
	global_store_dwordx4 v[60:61], v[30:33], off
	v_lshl_add_u64 v[60:61], v[76:77], 0, v[0:1]
	v_or_b32_e32 v0, v98, v47
	s_waitcnt lgkmcnt(6)
	v_cvt_pk_bf16_f32 v30, v64, v62
	s_waitcnt lgkmcnt(4)
	v_cvt_pk_bf16_f32 v31, v66, v68
	s_waitcnt lgkmcnt(2)
	v_cvt_pk_bf16_f32 v32, v70, v72
	s_waitcnt lgkmcnt(0)
	v_cvt_pk_bf16_f32 v33, v74, v78
	v_lshlrev_b32_e32 v0, 9, v0
	global_store_dwordx4 v[60:61], v[30:33], off
	v_lshl_add_u64 v[60:61], v[76:77], 0, v[0:1]
	s_nop 0
	v_cvt_pk_bf16_f32 v30, v65, v63
	v_cvt_pk_bf16_f32 v31, v67, v69
	v_cvt_pk_bf16_f32 v32, v71, v73
	v_cvt_pk_bf16_f32 v33, v75, v79
	global_store_dwordx4 v[60:61], v[30:33], off
	s_waitcnt lgkmcnt(0)

.LBB0_142:
	s_andn2_saveexec_b64 s[24:25], s[24:25]
	s_cbranch_execz .LBB0_144
	v_and_b32_e32 v74, 0x1ffc0, v58
	v_and_b32_e32 v80, 0x3e0, v56
	v_or_b32_e32 v32, v74, v41
	v_lshlrev_b32_e32 v0, 2, v80
	v_lshl_add_u64 v[30:31], v[8:9], 0, v[0:1]
	v_lshlrev_b32_e32 v0, 12, v32
	v_lshl_add_u64 v[30:31], v[30:31], 0, v[0:1]
	v_add_co_u32_e32 v32, vcc, 0x2000, v30
	s_nop 1
	v_addc_co_u32_e32 v33, vcc, 0, v31, vcc
	v_add_co_u32_e32 v60, vcc, 0x4000, v30
	s_nop 1
	v_addc_co_u32_e32 v61, vcc, 0, v31, vcc
	v_add_co_u32_e32 v62, vcc, 0x6000, v30
	s_nop 1
	v_addc_co_u32_e32 v63, vcc, 0, v31, vcc
	v_add_co_u32_e32 v64, vcc, s3, v30
	s_nop 1
	v_addc_co_u32_e32 v65, vcc, 0, v31, vcc
	v_add_co_u32_e32 v66, vcc, 0xa000, v30
	s_nop 1
	v_addc_co_u32_e32 v67, vcc, 0, v31, vcc
	v_add_co_u32_e32 v68, vcc, 0xc000, v30
	s_nop 1
	v_addc_co_u32_e32 v69, vcc, 0, v31, vcc
	v_add_co_u32_e32 v70, vcc, 0xe000, v30
	s_nop 1
	v_addc_co_u32_e32 v71, vcc, 0, v31, vcc
	global_load_dword v0, v[30:31], off nt
	global_load_dword v75, v[32:33], off nt
	global_load_dword v76, v[60:61], off nt
	global_load_dword v77, v[62:63], off nt
	global_load_dword v78, v[64:65], off nt
	global_load_dword v79, v[66:67], off nt
	global_load_dword v81, v[68:69], off nt
	global_load_dword v82, v[70:71], off nt
	v_add_co_u32_e32 v32, vcc, s30, v30
	s_nop 1
	v_addc_co_u32_e32 v33, vcc, 0, v31, vcc
	v_add_co_u32_e32 v60, vcc, 0x12000, v30
	s_nop 1
	v_addc_co_u32_e32 v61, vcc, 0, v31, vcc
	v_add_co_u32_e32 v62, vcc, 0x14000, v30
	s_nop 1
	v_addc_co_u32_e32 v63, vcc, 0, v31, vcc
	v_add_co_u32_e32 v64, vcc, 0x16000, v30
	s_nop 1
	v_addc_co_u32_e32 v65, vcc, 0, v31, vcc
	v_add_co_u32_e32 v66, vcc, s31, v30
	s_nop 1
	v_addc_co_u32_e32 v67, vcc, 0, v31, vcc
	v_add_co_u32_e32 v68, vcc, 0x1a000, v30
	s_nop 1
	v_addc_co_u32_e32 v69, vcc, 0, v31, vcc
	v_add_co_u32_e32 v70, vcc, 0x1c000, v30
	s_nop 1
	v_addc_co_u32_e32 v71, vcc, 0, v31, vcc
	v_add_co_u32_e32 v72, vcc, 0x1e000, v30
	s_nop 1
	v_addc_co_u32_e32 v73, vcc, 0, v31, vcc
	global_load_dword v83, v[32:33], off nt
	global_load_dword v84, v[60:61], off nt
	global_load_dword v85, v[62:63], off nt
	global_load_dword v86, v[64:65], off nt
	global_load_dword v87, v[66:67], off nt
	global_load_dword v88, v[68:69], off nt
	global_load_dword v89, v[70:71], off nt
	global_load_dword v90, v[72:73], off nt
	v_add_co_u32_e32 v32, vcc, s33, v30
	s_nop 1
	v_addc_co_u32_e32 v33, vcc, 0, v31, vcc
	v_add_co_u32_e32 v60, vcc, 0x22000, v30
	s_nop 1
	v_addc_co_u32_e32 v61, vcc, 0, v31, vcc
	v_add_co_u32_e32 v62, vcc, 0x24000, v30
	s_nop 1
	v_addc_co_u32_e32 v63, vcc, 0, v31, vcc
	v_add_co_u32_e32 v64, vcc, 0x26000, v30
	s_nop 1
	v_addc_co_u32_e32 v65, vcc, 0, v31, vcc
	v_add_co_u32_e32 v66, vcc, s40, v30
	s_nop 1
	v_addc_co_u32_e32 v67, vcc, 0, v31, vcc
	v_add_co_u32_e32 v68, vcc, 0x2a000, v30
	s_nop 1
	v_addc_co_u32_e32 v69, vcc, 0, v31, vcc
	v_add_co_u32_e32 v70, vcc, 0x2c000, v30
	s_nop 1
	v_addc_co_u32_e32 v71, vcc, 0, v31, vcc
	v_add_co_u32_e32 v72, vcc, 0x2e000, v30
	s_nop 1
	v_addc_co_u32_e32 v73, vcc, 0, v31, vcc
	global_load_dword v91, v[32:33], off nt
	global_load_dword v92, v[60:61], off nt
	global_load_dword v93, v[62:63], off nt
	global_load_dword v94, v[64:65], off nt
	global_load_dword v95, v[66:67], off nt
	global_load_dword v96, v[68:69], off nt
	global_load_dword v97, v[70:71], off nt
	s_nop 0
	global_load_dword v72, v[72:73], off nt
	v_add_co_u32_e32 v32, vcc, s41, v30
	s_nop 1
	v_addc_co_u32_e32 v33, vcc, 0, v31, vcc
	v_add_co_u32_e32 v60, vcc, 0x32000, v30
	s_nop 1
	v_addc_co_u32_e32 v61, vcc, 0, v31, vcc
	v_add_co_u32_e32 v62, vcc, 0x34000, v30
	s_nop 1
	v_addc_co_u32_e32 v63, vcc, 0, v31, vcc
	v_add_co_u32_e32 v64, vcc, 0x36000, v30
	s_nop 1
	v_addc_co_u32_e32 v65, vcc, 0, v31, vcc
	v_add_co_u32_e32 v66, vcc, s42, v30
	s_nop 1
	v_addc_co_u32_e32 v67, vcc, 0, v31, vcc
	v_add_co_u32_e32 v68, vcc, 0x3a000, v30
	s_nop 1
	v_addc_co_u32_e32 v69, vcc, 0, v31, vcc
	v_add_co_u32_e32 v70, vcc, 0x3c000, v30
	s_nop 1
	v_addc_co_u32_e32 v71, vcc, 0, v31, vcc
	v_add_co_u32_e32 v30, vcc, 0x3e000, v30
	s_nop 1
	v_addc_co_u32_e32 v31, vcc, 0, v31, vcc
	global_load_dword v32, v[32:33], off nt
	s_nop 0
	global_load_dword v33, v[60:61], off nt
	s_nop 0
	global_load_dword v60, v[62:63], off nt
	global_load_dword v61, v[64:65], off nt
	s_nop 0
	global_load_dword v62, v[66:67], off nt
	global_load_dword v63, v[68:69], off nt
	global_load_dword v64, v[70:71], off nt
	s_nop 0
	global_load_dword v30, v[30:31], off nt
	s_waitcnt vmcnt(30)
	ds_write2_b32 v42, v0, v75 offset1:66
	s_waitcnt vmcnt(28)
	ds_write2_b32 v42, v76, v77 offset0:132 offset1:198
	v_add_u32_e32 v0, 0x400, v42
	s_waitcnt vmcnt(26)
	ds_write2_b32 v0, v78, v79 offset0:8 offset1:74
	s_waitcnt vmcnt(24)
	ds_write2_b32 v0, v81, v82 offset0:140 offset1:206
	v_add_u32_e32 v0, 0x800, v42
	s_waitcnt vmcnt(22)
	ds_write2_b32 v0, v83, v84 offset0:16 offset1:82
	s_waitcnt vmcnt(20)
	ds_write2_b32 v0, v85, v86 offset0:148 offset1:214
	v_add_u32_e32 v0, 0xc00, v42
	s_waitcnt vmcnt(18)
	ds_write2_b32 v0, v87, v88 offset0:24 offset1:90
	s_waitcnt vmcnt(16)
	ds_write2_b32 v0, v89, v90 offset0:156 offset1:222
	v_add_u32_e32 v0, 0x1000, v42
	s_waitcnt vmcnt(14)
	ds_write2_b32 v0, v91, v92 offset0:32 offset1:98
	s_waitcnt vmcnt(12)
	ds_write2_b32 v0, v93, v94 offset0:164 offset1:230
	v_add_u32_e32 v0, 0x1400, v42
	s_waitcnt vmcnt(10)
	ds_write2_b32 v0, v95, v96 offset0:40 offset1:106
	s_waitcnt vmcnt(8)
	ds_write2_b32 v0, v97, v72 offset0:172 offset1:238
	v_add_u32_e32 v0, 0x1800, v42
	s_waitcnt vmcnt(6)
	ds_write2_b32 v0, v32, v33 offset0:48 offset1:114
	s_waitcnt vmcnt(4)
	ds_write2_b32 v0, v60, v61 offset0:180 offset1:246
	v_add_u32_e32 v0, 0x1c00, v42
	s_waitcnt vmcnt(2)
	ds_write2_b32 v0, v62, v63 offset0:56 offset1:122
	s_waitcnt vmcnt(0)
	ds_write2_b32 v0, v64, v30 offset0:188 offset1:254
	s_waitcnt lgkmcnt(0)
	v_lshlrev_b32_e32 v0, 1, v74
	ds_read2_b32 v[60:61], v44 offset0:33 offset1:41
	ds_read2_b32 v[62:63], v44 offset1:8
	ds_read2_b32 v[64:65], v44 offset0:66 offset1:74
	ds_read2_b32 v[66:67], v44 offset0:99 offset1:107
	ds_read2_b32 v[68:69], v44 offset0:132 offset1:140
	ds_read2_b32 v[70:71], v44 offset0:165 offset1:173
	ds_read2_b32 v[72:73], v44 offset0:198 offset1:206
	ds_read2_b32 v[74:75], v44 offset0:231 offset1:239
	v_lshl_add_u64 v[76:77], v[24:25], 0, v[0:1]
	v_or_b32_e32 v0, v80, v43
	v_lshlrev_b32_e32 v0, 11, v0
	s_waitcnt lgkmcnt(6)
	v_cvt_pk_bf16_f32 v30, v62, v60
	s_waitcnt lgkmcnt(4)
	v_cvt_pk_bf16_f32 v31, v64, v66
	s_waitcnt lgkmcnt(2)
	v_cvt_pk_bf16_f32 v32, v68, v70
	s_waitcnt lgkmcnt(0)
	v_cvt_pk_bf16_f32 v33, v72, v74
	v_lshl_add_u64 v[78:79], v[76:77], 0, v[0:1]
	global_store_dwordx4 v[78:79], v[30:33], off
	v_or_b32_e32 v0, v80, v45
	v_lshlrev_b32_e32 v0, 11, v0
	v_cvt_pk_bf16_f32 v30, v63, v61
	v_cvt_pk_bf16_f32 v31, v65, v67
	v_cvt_pk_bf16_f32 v32, v69, v71
	v_cvt_pk_bf16_f32 v33, v73, v75
	ds_read2_b32 v[62:63], v44 offset0:49 offset1:57
	ds_read2_b32 v[64:65], v44 offset0:16 offset1:24
	ds_read2_b32 v[66:67], v44 offset0:82 offset1:90
	ds_read2_b32 v[68:69], v44 offset0:115 offset1:123
	ds_read2_b32 v[70:71], v44 offset0:148 offset1:156
	ds_read2_b32 v[72:73], v44 offset0:181 offset1:189
	ds_read2_b32 v[74:75], v44 offset0:214 offset1:222
	ds_read2_b32 v[78:79], v44 offset0:247 offset1:255
	v_lshl_add_u64 v[60:61], v[76:77], 0, v[0:1]
	v_or_b32_e32 v0, v80, v46
	v_lshlrev_b32_e32 v0, 11, v0
	global_store_dwordx4 v[60:61], v[30:33], off
	v_lshl_add_u64 v[60:61], v[76:77], 0, v[0:1]
	v_or_b32_e32 v0, v80, v47
	s_waitcnt lgkmcnt(6)
	v_cvt_pk_bf16_f32 v30, v64, v62
	s_waitcnt lgkmcnt(4)
	v_cvt_pk_bf16_f32 v31, v66, v68
	s_waitcnt lgkmcnt(2)
	v_cvt_pk_bf16_f32 v32, v70, v72
	s_waitcnt lgkmcnt(0)
	v_cvt_pk_bf16_f32 v33, v74, v78
	v_lshlrev_b32_e32 v0, 11, v0
	global_store_dwordx4 v[60:61], v[30:33], off
	v_lshl_add_u64 v[60:61], v[76:77], 0, v[0:1]
	s_nop 0
	v_cvt_pk_bf16_f32 v30, v65, v63
	v_cvt_pk_bf16_f32 v31, v67, v69
	v_cvt_pk_bf16_f32 v32, v71, v73
	v_cvt_pk_bf16_f32 v33, v75, v79
	global_store_dwordx4 v[60:61], v[30:33], off
	s_waitcnt lgkmcnt(0)

.LBB0_145:
	s_andn2_saveexec_b64 s[14:15], s[14:15]
	s_cbranch_execz .LBB0_147
	v_add_u32_e32 v0, 0x400, v58
	v_and_b32_e32 v74, 0x1ffc0, v0
	v_and_b32_e32 v80, 0x3e0, v56
	v_or_b32_e32 v32, v74, v41
	v_lshlrev_b32_e32 v0, 2, v80
	v_lshl_add_u64 v[30:31], v[10:11], 0, v[0:1]
	v_lshlrev_b32_e32 v0, 12, v32
	v_lshl_add_u64 v[30:31], v[30:31], 0, v[0:1]
	v_add_co_u32_e32 v32, vcc, 0x2000, v30
	s_nop 1
	v_addc_co_u32_e32 v33, vcc, 0, v31, vcc
	v_add_co_u32_e32 v60, vcc, 0x4000, v30
	s_nop 1
	v_addc_co_u32_e32 v61, vcc, 0, v31, vcc
	v_add_co_u32_e32 v62, vcc, 0x6000, v30
	s_nop 1
	v_addc_co_u32_e32 v63, vcc, 0, v31, vcc
	v_add_co_u32_e32 v64, vcc, s3, v30
	s_nop 1
	v_addc_co_u32_e32 v65, vcc, 0, v31, vcc
	v_add_co_u32_e32 v66, vcc, 0xa000, v30
	s_nop 1
	v_addc_co_u32_e32 v67, vcc, 0, v31, vcc
	v_add_co_u32_e32 v68, vcc, 0xc000, v30
	s_nop 1
	v_addc_co_u32_e32 v69, vcc, 0, v31, vcc
	v_add_co_u32_e32 v70, vcc, 0xe000, v30
	s_nop 1
	v_addc_co_u32_e32 v71, vcc, 0, v31, vcc
	global_load_dword v0, v[30:31], off nt
	global_load_dword v75, v[32:33], off nt
	global_load_dword v76, v[60:61], off nt
	global_load_dword v77, v[62:63], off nt
	global_load_dword v78, v[64:65], off nt
	global_load_dword v79, v[66:67], off nt
	global_load_dword v81, v[68:69], off nt
	global_load_dword v82, v[70:71], off nt
	v_add_co_u32_e32 v32, vcc, s30, v30
	s_nop 1
	v_addc_co_u32_e32 v33, vcc, 0, v31, vcc
	v_add_co_u32_e32 v60, vcc, 0x12000, v30
	s_nop 1
	v_addc_co_u32_e32 v61, vcc, 0, v31, vcc
	v_add_co_u32_e32 v62, vcc, 0x14000, v30
	s_nop 1
	v_addc_co_u32_e32 v63, vcc, 0, v31, vcc
	v_add_co_u32_e32 v64, vcc, 0x16000, v30
	s_nop 1
	v_addc_co_u32_e32 v65, vcc, 0, v31, vcc
	v_add_co_u32_e32 v66, vcc, s31, v30
	s_nop 1
	v_addc_co_u32_e32 v67, vcc, 0, v31, vcc
	v_add_co_u32_e32 v68, vcc, 0x1a000, v30
	s_nop 1
	v_addc_co_u32_e32 v69, vcc, 0, v31, vcc
	v_add_co_u32_e32 v70, vcc, 0x1c000, v30
	s_nop 1
	v_addc_co_u32_e32 v71, vcc, 0, v31, vcc
	v_add_co_u32_e32 v72, vcc, 0x1e000, v30
	s_nop 1
	v_addc_co_u32_e32 v73, vcc, 0, v31, vcc
	global_load_dword v83, v[32:33], off nt
	global_load_dword v84, v[60:61], off nt
	global_load_dword v85, v[62:63], off nt
	global_load_dword v86, v[64:65], off nt
	global_load_dword v87, v[66:67], off nt
	global_load_dword v88, v[68:69], off nt
	global_load_dword v89, v[70:71], off nt
	global_load_dword v90, v[72:73], off nt
	v_add_co_u32_e32 v32, vcc, s33, v30
	s_nop 1
	v_addc_co_u32_e32 v33, vcc, 0, v31, vcc
	v_add_co_u32_e32 v60, vcc, 0x22000, v30
	s_nop 1
	v_addc_co_u32_e32 v61, vcc, 0, v31, vcc
	v_add_co_u32_e32 v62, vcc, 0x24000, v30
	s_nop 1
	v_addc_co_u32_e32 v63, vcc, 0, v31, vcc
	v_add_co_u32_e32 v64, vcc, 0x26000, v30
	s_nop 1
	v_addc_co_u32_e32 v65, vcc, 0, v31, vcc
	v_add_co_u32_e32 v66, vcc, s40, v30
	s_nop 1
	v_addc_co_u32_e32 v67, vcc, 0, v31, vcc
	v_add_co_u32_e32 v68, vcc, 0x2a000, v30
	s_nop 1
	v_addc_co_u32_e32 v69, vcc, 0, v31, vcc
	v_add_co_u32_e32 v70, vcc, 0x2c000, v30
	s_nop 1
	v_addc_co_u32_e32 v71, vcc, 0, v31, vcc
	v_add_co_u32_e32 v72, vcc, 0x2e000, v30
	s_nop 1
	v_addc_co_u32_e32 v73, vcc, 0, v31, vcc
	global_load_dword v91, v[32:33], off nt
	global_load_dword v92, v[60:61], off nt
	global_load_dword v93, v[62:63], off nt
	global_load_dword v94, v[64:65], off nt
	global_load_dword v95, v[66:67], off nt
	global_load_dword v96, v[68:69], off nt
	global_load_dword v97, v[70:71], off nt
	s_nop 0
	global_load_dword v72, v[72:73], off nt
	v_add_co_u32_e32 v32, vcc, s41, v30
	s_nop 1
	v_addc_co_u32_e32 v33, vcc, 0, v31, vcc
	v_add_co_u32_e32 v60, vcc, 0x32000, v30
	s_nop 1
	v_addc_co_u32_e32 v61, vcc, 0, v31, vcc
	v_add_co_u32_e32 v62, vcc, 0x34000, v30
	s_nop 1
	v_addc_co_u32_e32 v63, vcc, 0, v31, vcc
	v_add_co_u32_e32 v64, vcc, 0x36000, v30
	s_nop 1
	v_addc_co_u32_e32 v65, vcc, 0, v31, vcc
	v_add_co_u32_e32 v66, vcc, s42, v30
	s_nop 1
	v_addc_co_u32_e32 v67, vcc, 0, v31, vcc
	v_add_co_u32_e32 v68, vcc, 0x3a000, v30
	s_nop 1
	v_addc_co_u32_e32 v69, vcc, 0, v31, vcc
	v_add_co_u32_e32 v70, vcc, 0x3c000, v30
	s_nop 1
	v_addc_co_u32_e32 v71, vcc, 0, v31, vcc
	v_add_co_u32_e32 v30, vcc, 0x3e000, v30
	s_nop 1
	v_addc_co_u32_e32 v31, vcc, 0, v31, vcc
	global_load_dword v32, v[32:33], off nt
	s_nop 0
	global_load_dword v33, v[60:61], off nt
	s_nop 0
	global_load_dword v60, v[62:63], off nt
	global_load_dword v61, v[64:65], off nt
	s_nop 0
	global_load_dword v62, v[66:67], off nt
	global_load_dword v63, v[68:69], off nt
	global_load_dword v64, v[70:71], off nt
	s_nop 0
	global_load_dword v30, v[30:31], off nt
	s_waitcnt vmcnt(30)
	ds_write2_b32 v42, v0, v75 offset1:66
	s_waitcnt vmcnt(28)
	ds_write2_b32 v42, v76, v77 offset0:132 offset1:198
	v_add_u32_e32 v0, 0x400, v42
	s_waitcnt vmcnt(26)
	ds_write2_b32 v0, v78, v79 offset0:8 offset1:74
	s_waitcnt vmcnt(24)
	ds_write2_b32 v0, v81, v82 offset0:140 offset1:206
	v_add_u32_e32 v0, 0x800, v42
	s_waitcnt vmcnt(22)
	ds_write2_b32 v0, v83, v84 offset0:16 offset1:82
	s_waitcnt vmcnt(20)
	ds_write2_b32 v0, v85, v86 offset0:148 offset1:214
	v_add_u32_e32 v0, 0xc00, v42
	s_waitcnt vmcnt(18)
	ds_write2_b32 v0, v87, v88 offset0:24 offset1:90
	s_waitcnt vmcnt(16)
	ds_write2_b32 v0, v89, v90 offset0:156 offset1:222
	v_add_u32_e32 v0, 0x1000, v42
	s_waitcnt vmcnt(14)
	ds_write2_b32 v0, v91, v92 offset0:32 offset1:98
	s_waitcnt vmcnt(12)
	ds_write2_b32 v0, v93, v94 offset0:164 offset1:230
	v_add_u32_e32 v0, 0x1400, v42
	s_waitcnt vmcnt(10)
	ds_write2_b32 v0, v95, v96 offset0:40 offset1:106
	s_waitcnt vmcnt(8)
	ds_write2_b32 v0, v97, v72 offset0:172 offset1:238
	v_add_u32_e32 v0, 0x1800, v42
	s_waitcnt vmcnt(6)
	ds_write2_b32 v0, v32, v33 offset0:48 offset1:114
	s_waitcnt vmcnt(4)
	ds_write2_b32 v0, v60, v61 offset0:180 offset1:246
	v_add_u32_e32 v0, 0x1c00, v42
	s_waitcnt vmcnt(2)
	ds_write2_b32 v0, v62, v63 offset0:56 offset1:122
	s_waitcnt vmcnt(0)
	ds_write2_b32 v0, v64, v30 offset0:188 offset1:254
	s_waitcnt lgkmcnt(0)
	v_lshlrev_b32_e32 v0, 1, v74
	ds_read2_b32 v[60:61], v44 offset0:33 offset1:41
	ds_read2_b32 v[62:63], v44 offset1:8
	ds_read2_b32 v[64:65], v44 offset0:66 offset1:74
	ds_read2_b32 v[66:67], v44 offset0:99 offset1:107
	ds_read2_b32 v[68:69], v44 offset0:132 offset1:140
	ds_read2_b32 v[70:71], v44 offset0:165 offset1:173
	ds_read2_b32 v[72:73], v44 offset0:198 offset1:206
	ds_read2_b32 v[74:75], v44 offset0:231 offset1:239
	v_lshl_add_u64 v[76:77], v[26:27], 0, v[0:1]
	v_or_b32_e32 v0, v80, v43
	v_lshlrev_b32_e32 v0, 11, v0
	s_waitcnt lgkmcnt(6)
	v_cvt_pk_bf16_f32 v30, v62, v60
	s_waitcnt lgkmcnt(4)
	v_cvt_pk_bf16_f32 v31, v64, v66
	s_waitcnt lgkmcnt(2)
	v_cvt_pk_bf16_f32 v32, v68, v70
	s_waitcnt lgkmcnt(0)
	v_cvt_pk_bf16_f32 v33, v72, v74
	v_lshl_add_u64 v[78:79], v[76:77], 0, v[0:1]
	global_store_dwordx4 v[78:79], v[30:33], off
	v_or_b32_e32 v0, v80, v45
	v_lshlrev_b32_e32 v0, 11, v0
	v_cvt_pk_bf16_f32 v30, v63, v61
	v_cvt_pk_bf16_f32 v31, v65, v67
	v_cvt_pk_bf16_f32 v32, v69, v71
	v_cvt_pk_bf16_f32 v33, v73, v75
	ds_read2_b32 v[62:63], v44 offset0:49 offset1:57
	ds_read2_b32 v[64:65], v44 offset0:16 offset1:24
	ds_read2_b32 v[66:67], v44 offset0:82 offset1:90
	ds_read2_b32 v[68:69], v44 offset0:115 offset1:123
	ds_read2_b32 v[70:71], v44 offset0:148 offset1:156
	ds_read2_b32 v[72:73], v44 offset0:181 offset1:189
	ds_read2_b32 v[74:75], v44 offset0:214 offset1:222
	ds_read2_b32 v[78:79], v44 offset0:247 offset1:255
	v_lshl_add_u64 v[60:61], v[76:77], 0, v[0:1]
	v_or_b32_e32 v0, v80, v46
	v_lshlrev_b32_e32 v0, 11, v0
	global_store_dwordx4 v[60:61], v[30:33], off
	v_lshl_add_u64 v[60:61], v[76:77], 0, v[0:1]
	v_or_b32_e32 v0, v80, v47
	s_waitcnt lgkmcnt(6)
	v_cvt_pk_bf16_f32 v30, v64, v62
	s_waitcnt lgkmcnt(4)
	v_cvt_pk_bf16_f32 v31, v66, v68
	s_waitcnt lgkmcnt(2)
	v_cvt_pk_bf16_f32 v32, v70, v72
	s_waitcnt lgkmcnt(0)
	v_cvt_pk_bf16_f32 v33, v74, v78
	v_lshlrev_b32_e32 v0, 11, v0
	global_store_dwordx4 v[60:61], v[30:33], off
	v_lshl_add_u64 v[60:61], v[76:77], 0, v[0:1]
	s_nop 0
	v_cvt_pk_bf16_f32 v30, v65, v63
	v_cvt_pk_bf16_f32 v31, v67, v69
	v_cvt_pk_bf16_f32 v32, v71, v73
	v_cvt_pk_bf16_f32 v33, v75, v79
	global_store_dwordx4 v[60:61], v[30:33], off
	s_waitcnt lgkmcnt(0)

.LBB0_148:
	s_andn2_saveexec_b64 s[14:15], s[6:7]
	s_cbranch_execz .LBB0_214
	v_add_u16_e32 v0, 0xf800, v53
	v_mul_u32_u24_e32 v30, 0xe38f, v0
	v_lshrrev_b32_e32 v33, 16, v30
	v_lshrrev_b32_e32 v30, 22, v30
	v_mul_lo_u16_e32 v30, 0x48, v30
	v_sub_u16_e32 v0, v0, v30
	v_lshlrev_b16_e32 v32, 5, v0
	v_cmp_gt_u16_e64 s[6:7], s95, v0
	v_and_or_b32 v60, v33, s96, v41
	v_lshlrev_b32_e32 v0, 2, v32
	v_lshl_add_u64 v[30:31], v[12:13], 0, v[0:1]
	v_mul_u32_u24_e32 v0, 0x8a0, v60
	v_mov_b32_e32 v61, 0
	v_lshlrev_b32_e32 v0, 2, v0
	v_mov_b32_e32 v60, 0
	s_and_saveexec_b64 s[24:25], s[6:7]
	s_cbranch_execz .LBB0_151
	v_lshl_add_u64 v[62:63], v[30:31], 0, v[0:1]
	global_load_dword v60, v[62:63], off nt
.LBB0_151:
	s_or_b64 exec, exec, s[24:25]
	s_and_saveexec_b64 s[24:25], s[6:7]
	s_cbranch_execz .LBB0_153
	v_lshl_add_u64 v[62:63], v[30:31], 0, v[0:1]
	v_add_co_u32_e32 v62, vcc, 0x4000, v62
	s_nop 1
	v_addc_co_u32_e32 v63, vcc, 0, v63, vcc
	global_load_dword v61, v[62:63], off offset:1280 nt
.LBB0_153:
	s_or_b64 exec, exec, s[24:25]
	v_mov_b32_e32 v62, 0
	v_mov_b32_e32 v63, 0
	s_and_saveexec_b64 s[24:25], s[6:7]
	s_cbranch_execz .LBB0_155
	v_lshl_add_u64 v[64:65], v[30:31], 0, v[0:1]
	v_add_co_u32_e32 v64, vcc, 0x8000, v64
	s_nop 1
	v_addc_co_u32_e32 v65, vcc, 0, v65, vcc
	global_load_dword v63, v[64:65], off offset:2560 nt
.LBB0_155:
	s_or_b64 exec, exec, s[24:25]
	s_and_saveexec_b64 s[24:25], s[6:7]
	s_cbranch_execz .LBB0_157
	v_lshl_add_u64 v[64:65], v[30:31], 0, v[0:1]
	v_add_co_u32_e32 v64, vcc, 0xc000, v64
	s_nop 1
	v_addc_co_u32_e32 v65, vcc, 0, v65, vcc
	global_load_dword v62, v[64:65], off offset:3840 nt
.LBB0_157:
	s_or_b64 exec, exec, s[24:25]
	v_mov_b32_e32 v64, 0
	v_mov_b32_e32 v65, 0
	s_and_saveexec_b64 s[24:25], s[6:7]
	s_cbranch_execz .LBB0_159
	v_lshl_add_u64 v[66:67], v[30:31], 0, v[0:1]
	v_add_co_u32_e32 v66, vcc, 0x11000, v66
	s_nop 1
	v_addc_co_u32_e32 v67, vcc, 0, v67, vcc
	global_load_dword v65, v[66:67], off offset:1024 nt
.LBB0_159:
	s_or_b64 exec, exec, s[24:25]
	s_and_saveexec_b64 s[24:25], s[6:7]
	s_cbranch_execz .LBB0_161
	v_lshl_add_u64 v[66:67], v[30:31], 0, v[0:1]
	v_add_co_u32_e32 v66, vcc, 0x15000, v66
	s_nop 1
	v_addc_co_u32_e32 v67, vcc, 0, v67, vcc
	global_load_dword v64, v[66:67], off offset:2304 nt
.LBB0_161:
	s_or_b64 exec, exec, s[24:25]
	v_mov_b32_e32 v66, 0
	v_mov_b32_e32 v67, 0
	s_and_saveexec_b64 s[24:25], s[6:7]
	s_cbranch_execz .LBB0_163
	v_lshl_add_u64 v[68:69], v[30:31], 0, v[0:1]
	v_add_co_u32_e32 v68, vcc, 0x19000, v68
	s_nop 1
	v_addc_co_u32_e32 v69, vcc, 0, v69, vcc
	global_load_dword v67, v[68:69], off offset:3584 nt
.LBB0_163:
	s_or_b64 exec, exec, s[24:25]
	s_and_saveexec_b64 s[24:25], s[6:7]
	s_cbranch_execz .LBB0_165
	v_lshl_add_u64 v[68:69], v[30:31], 0, v[0:1]
	v_add_co_u32_e32 v68, vcc, 0x1e000, v68
	s_nop 1
	v_addc_co_u32_e32 v69, vcc, 0, v69, vcc
	global_load_dword v66, v[68:69], off offset:768 nt
.LBB0_165:
	s_or_b64 exec, exec, s[24:25]
	v_mov_b32_e32 v68, 0
	v_mov_b32_e32 v69, 0
	s_and_saveexec_b64 s[24:25], s[6:7]
	s_cbranch_execz .LBB0_167
	v_lshl_add_u64 v[70:71], v[30:31], 0, v[0:1]
	v_add_co_u32_e32 v70, vcc, 0x22000, v70
	s_nop 1
	v_addc_co_u32_e32 v71, vcc, 0, v71, vcc
	global_load_dword v69, v[70:71], off offset:2048 nt
.LBB0_167:
	s_or_b64 exec, exec, s[24:25]
	s_and_saveexec_b64 s[24:25], s[6:7]
	s_cbranch_execz .LBB0_169
	v_lshl_add_u64 v[70:71], v[30:31], 0, v[0:1]
	v_add_co_u32_e32 v70, vcc, 0x26000, v70
	s_nop 1
	v_addc_co_u32_e32 v71, vcc, 0, v71, vcc
	global_load_dword v68, v[70:71], off offset:3328 nt
.LBB0_169:
	s_or_b64 exec, exec, s[24:25]
	v_mov_b32_e32 v70, 0
	v_mov_b32_e32 v71, 0
	s_and_saveexec_b64 s[24:25], s[6:7]
	s_cbranch_execz .LBB0_171
	v_lshl_add_u64 v[72:73], v[30:31], 0, v[0:1]
	v_add_co_u32_e32 v72, vcc, 0x2b000, v72
	s_nop 1
	v_addc_co_u32_e32 v73, vcc, 0, v73, vcc
	global_load_dword v71, v[72:73], off offset:512 nt
.LBB0_171:
	s_or_b64 exec, exec, s[24:25]
	s_and_saveexec_b64 s[24:25], s[6:7]
	s_cbranch_execz .LBB0_173
	v_lshl_add_u64 v[72:73], v[30:31], 0, v[0:1]
	v_add_co_u32_e32 v72, vcc, 0x2f000, v72
	s_nop 1
	v_addc_co_u32_e32 v73, vcc, 0, v73, vcc
	global_load_dword v70, v[72:73], off offset:1792 nt
.LBB0_173:
	s_or_b64 exec, exec, s[24:25]
	v_mov_b32_e32 v72, 0
	v_mov_b32_e32 v73, 0
	s_and_saveexec_b64 s[24:25], s[6:7]
	s_cbranch_execz .LBB0_175
	v_lshl_add_u64 v[74:75], v[30:31], 0, v[0:1]
	v_add_co_u32_e32 v74, vcc, 0x33000, v74
	s_nop 1
	v_addc_co_u32_e32 v75, vcc, 0, v75, vcc
	global_load_dword v73, v[74:75], off offset:3072 nt
.LBB0_175:
	s_or_b64 exec, exec, s[24:25]
	s_and_saveexec_b64 s[24:25], s[6:7]
	s_cbranch_execz .LBB0_177
	v_lshl_add_u64 v[74:75], v[30:31], 0, v[0:1]
	v_add_co_u32_e32 v74, vcc, 0x38000, v74
	s_nop 1
	v_addc_co_u32_e32 v75, vcc, 0, v75, vcc
	global_load_dword v72, v[74:75], off offset:256 nt
.LBB0_177:
	s_or_b64 exec, exec, s[24:25]
	v_mov_b32_e32 v74, 0
	v_mov_b32_e32 v75, 0
	s_and_saveexec_b64 s[24:25], s[6:7]
	s_cbranch_execz .LBB0_179
	v_lshl_add_u64 v[76:77], v[30:31], 0, v[0:1]
	v_add_co_u32_e32 v76, vcc, 0x3c000, v76
	s_nop 1
	v_addc_co_u32_e32 v77, vcc, 0, v77, vcc
	global_load_dword v75, v[76:77], off offset:1536 nt
.LBB0_179:
	s_or_b64 exec, exec, s[24:25]
	s_and_saveexec_b64 s[24:25], s[6:7]
	s_cbranch_execz .LBB0_181
	v_lshl_add_u64 v[76:77], v[30:31], 0, v[0:1]
	v_add_co_u32_e32 v76, vcc, 0x40000, v76
	s_nop 1
	v_addc_co_u32_e32 v77, vcc, 0, v77, vcc
	global_load_dword v74, v[76:77], off offset:2816 nt
.LBB0_181:
	s_or_b64 exec, exec, s[24:25]
	v_mov_b32_e32 v76, 0
	v_mov_b32_e32 v77, 0
	s_and_saveexec_b64 s[24:25], s[6:7]
	s_cbranch_execz .LBB0_183
	v_lshl_add_u64 v[78:79], v[30:31], 0, v[0:1]
	v_add_co_u32_e32 v78, vcc, 0x45000, v78
	s_nop 1
	v_addc_co_u32_e32 v79, vcc, 0, v79, vcc
	global_load_dword v77, v[78:79], off nt
.LBB0_183:
	s_or_b64 exec, exec, s[24:25]
	s_and_saveexec_b64 s[24:25], s[6:7]
	s_cbranch_execz .LBB0_185
	v_lshl_add_u64 v[78:79], v[30:31], 0, v[0:1]
	v_add_co_u32_e32 v78, vcc, 0x49000, v78
	s_nop 1
	v_addc_co_u32_e32 v79, vcc, 0, v79, vcc
	global_load_dword v76, v[78:79], off offset:1280 nt
.LBB0_185:
	s_or_b64 exec, exec, s[24:25]
	v_mov_b32_e32 v78, 0
	v_mov_b32_e32 v79, 0
	s_and_saveexec_b64 s[24:25], s[6:7]
	s_cbranch_execz .LBB0_187
	v_lshl_add_u64 v[80:81], v[30:31], 0, v[0:1]
	v_add_co_u32_e32 v80, vcc, 0x4d000, v80
	s_nop 1
	v_addc_co_u32_e32 v81, vcc, 0, v81, vcc
	global_load_dword v79, v[80:81], off offset:2560 nt
.LBB0_187:
	s_or_b64 exec, exec, s[24:25]
	s_and_saveexec_b64 s[24:25], s[6:7]
	s_cbranch_execz .LBB0_189
	v_lshl_add_u64 v[80:81], v[30:31], 0, v[0:1]
	v_add_co_u32_e32 v80, vcc, 0x51000, v80
	s_nop 1
	v_addc_co_u32_e32 v81, vcc, 0, v81, vcc
	global_load_dword v78, v[80:81], off offset:3840 nt
.LBB0_189:
	s_or_b64 exec, exec, s[24:25]
	v_mov_b32_e32 v80, 0
	v_mov_b32_e32 v81, 0
	s_and_saveexec_b64 s[24:25], s[6:7]
	s_cbranch_execz .LBB0_191
	v_lshl_add_u64 v[82:83], v[30:31], 0, v[0:1]
	v_add_co_u32_e32 v82, vcc, 0x56000, v82
	s_nop 1
	v_addc_co_u32_e32 v83, vcc, 0, v83, vcc
	global_load_dword v81, v[82:83], off offset:1024 nt
.LBB0_191:
	s_or_b64 exec, exec, s[24:25]
	s_and_saveexec_b64 s[24:25], s[6:7]
	s_cbranch_execz .LBB0_193
	v_lshl_add_u64 v[82:83], v[30:31], 0, v[0:1]
	v_add_co_u32_e32 v82, vcc, 0x5a000, v82
	s_nop 1
	v_addc_co_u32_e32 v83, vcc, 0, v83, vcc
	global_load_dword v80, v[82:83], off offset:2304 nt
.LBB0_193:
	s_or_b64 exec, exec, s[24:25]
	v_mov_b32_e32 v82, 0
	v_mov_b32_e32 v83, 0
	s_and_saveexec_b64 s[24:25], s[6:7]
	s_cbranch_execz .LBB0_195
	v_lshl_add_u64 v[84:85], v[30:31], 0, v[0:1]
	v_add_co_u32_e32 v84, vcc, 0x5e000, v84
	s_nop 1
	v_addc_co_u32_e32 v85, vcc, 0, v85, vcc
	global_load_dword v83, v[84:85], off offset:3584 nt
.LBB0_195:
	s_or_b64 exec, exec, s[24:25]
	s_and_saveexec_b64 s[24:25], s[6:7]
	s_cbranch_execz .LBB0_197
	v_lshl_add_u64 v[84:85], v[30:31], 0, v[0:1]
	v_add_co_u32_e32 v84, vcc, 0x63000, v84
	s_nop 1
	v_addc_co_u32_e32 v85, vcc, 0, v85, vcc
	global_load_dword v82, v[84:85], off offset:768 nt
.LBB0_197:
	s_or_b64 exec, exec, s[24:25]
	v_mov_b32_e32 v84, 0
	v_mov_b32_e32 v85, 0
	s_and_saveexec_b64 s[24:25], s[6:7]
	s_cbranch_execz .LBB0_199
	v_lshl_add_u64 v[86:87], v[30:31], 0, v[0:1]
	v_add_co_u32_e32 v86, vcc, 0x67000, v86
	s_nop 1
	v_addc_co_u32_e32 v87, vcc, 0, v87, vcc
	global_load_dword v85, v[86:87], off offset:2048 nt
.LBB0_199:
	s_or_b64 exec, exec, s[24:25]
	s_and_saveexec_b64 s[24:25], s[6:7]
	s_cbranch_execz .LBB0_201
	v_lshl_add_u64 v[86:87], v[30:31], 0, v[0:1]
	v_add_co_u32_e32 v86, vcc, 0x6b000, v86
	s_nop 1
	v_addc_co_u32_e32 v87, vcc, 0, v87, vcc
	global_load_dword v84, v[86:87], off offset:3328 nt
.LBB0_201:
	s_or_b64 exec, exec, s[24:25]
	v_mov_b32_e32 v86, 0
	v_mov_b32_e32 v87, 0
	s_and_saveexec_b64 s[24:25], s[6:7]
	s_cbranch_execz .LBB0_203
	v_lshl_add_u64 v[88:89], v[30:31], 0, v[0:1]
	v_add_co_u32_e32 v88, vcc, 0x70000, v88
	s_nop 1
	v_addc_co_u32_e32 v89, vcc, 0, v89, vcc
	global_load_dword v87, v[88:89], off offset:512 nt
.LBB0_203:
	s_or_b64 exec, exec, s[24:25]
	s_and_saveexec_b64 s[24:25], s[6:7]
	s_cbranch_execz .LBB0_205
	v_lshl_add_u64 v[88:89], v[30:31], 0, v[0:1]
	v_add_co_u32_e32 v88, vcc, 0x74000, v88
	s_nop 1
	v_addc_co_u32_e32 v89, vcc, 0, v89, vcc
	global_load_dword v86, v[88:89], off offset:1792 nt
.LBB0_205:
	s_or_b64 exec, exec, s[24:25]
	v_mov_b32_e32 v88, 0
	v_mov_b32_e32 v89, 0
	s_and_saveexec_b64 s[24:25], s[6:7]
	s_cbranch_execz .LBB0_207
	v_lshl_add_u64 v[90:91], v[30:31], 0, v[0:1]
	v_add_co_u32_e32 v90, vcc, 0x78000, v90
	s_nop 1
	v_addc_co_u32_e32 v91, vcc, 0, v91, vcc
	global_load_dword v89, v[90:91], off offset:3072 nt
.LBB0_207:
	s_or_b64 exec, exec, s[24:25]
	s_and_saveexec_b64 s[24:25], s[6:7]
	s_cbranch_execz .LBB0_209
	v_lshl_add_u64 v[90:91], v[30:31], 0, v[0:1]
	v_add_co_u32_e32 v90, vcc, 0x7d000, v90
	s_nop 1
	v_addc_co_u32_e32 v91, vcc, 0, v91, vcc
	global_load_dword v88, v[90:91], off offset:256 nt
.LBB0_209:
	s_or_b64 exec, exec, s[24:25]
	v_mov_b32_e32 v90, 0
	v_mov_b32_e32 v91, 0
	s_and_saveexec_b64 s[24:25], s[6:7]
	s_cbranch_execz .LBB0_211
	v_lshl_add_u64 v[92:93], v[30:31], 0, v[0:1]
	v_add_co_u32_e32 v92, vcc, 0x81000, v92
	s_nop 1
	v_addc_co_u32_e32 v93, vcc, 0, v93, vcc
	global_load_dword v91, v[92:93], off offset:1536 nt
.LBB0_211:
	s_or_b64 exec, exec, s[24:25]
	s_and_saveexec_b64 s[24:25], s[6:7]
	s_cbranch_execz .LBB0_213
	v_lshl_add_u64 v[30:31], v[30:31], 0, v[0:1]
	v_add_co_u32_e32 v30, vcc, 0x85000, v30
	s_nop 1
	v_addc_co_u32_e32 v31, vcc, 0, v31, vcc
	global_load_dword v90, v[30:31], off offset:2816 nt

.LBB0_215:
	s_andn2_saveexec_b64 s[6:7], s[12:13]
	s_cbranch_execz .LBB0_128
	v_ashrrev_i32_e32 v0, 31, v53
	v_lshrrev_b32_e32 v0, 25, v0
	v_add_u32_e32 v0, v53, v0
	v_ashrrev_i32_e32 v0, 7, v0
	v_lshlrev_b32_e32 v32, 6, v0
	v_lshlrev_b32_e32 v0, 12, v0
	v_or_b32_e32 v60, v32, v41
	v_sub_u32_e32 v30, v56, v0
	v_or_b32_e32 v66, 2, v60
	v_or_b32_e32 v68, 4, v60
	v_or_b32_e32 v70, 6, v60
	v_or_b32_e32 v72, 8, v60
	v_or_b32_e32 v74, 10, v60
	v_or_b32_e32 v76, 12, v60
	v_or_b32_e32 v78, 14, v60
	v_ashrrev_i32_e32 v31, 31, v30
	v_ashrrev_i32_e32 v61, 31, v60
	v_ashrrev_i32_e32 v67, 31, v66
	v_ashrrev_i32_e32 v69, 31, v68
	v_ashrrev_i32_e32 v71, 31, v70
	v_ashrrev_i32_e32 v73, 31, v72
	v_ashrrev_i32_e32 v75, 31, v74
	v_ashrrev_i32_e32 v77, 31, v76
	v_ashrrev_i32_e32 v79, 31, v78
	v_lshl_add_u64 v[62:63], v[30:31], 2, v[16:17]
	v_lshlrev_b64 v[64:65], 14, v[60:61]
	v_lshlrev_b64 v[66:67], 14, v[66:67]
	v_lshlrev_b64 v[68:69], 14, v[68:69]
	v_lshlrev_b64 v[70:71], 14, v[70:71]
	v_lshlrev_b64 v[72:73], 14, v[72:73]
	v_lshlrev_b64 v[74:75], 14, v[74:75]
	v_lshlrev_b64 v[76:77], 14, v[76:77]
	v_lshlrev_b64 v[78:79], 14, v[78:79]
	v_lshl_add_u64 v[64:65], v[62:63], 0, v[64:65]
	v_lshl_add_u64 v[66:67], v[62:63], 0, v[66:67]
	v_lshl_add_u64 v[68:69], v[62:63], 0, v[68:69]
	v_lshl_add_u64 v[70:71], v[62:63], 0, v[70:71]
	v_lshl_add_u64 v[72:73], v[62:63], 0, v[72:73]
	v_lshl_add_u64 v[74:75], v[62:63], 0, v[74:75]
	v_lshl_add_u64 v[76:77], v[62:63], 0, v[76:77]
	v_lshl_add_u64 v[78:79], v[62:63], 0, v[78:79]
	global_load_dword v0, v[64:65], off nt
	global_load_dword v31, v[66:67], off nt
	global_load_dword v33, v[68:69], off nt
	global_load_dword v80, v[70:71], off nt
	global_load_dword v81, v[72:73], off nt
	global_load_dword v82, v[74:75], off nt
	global_load_dword v83, v[76:77], off nt
	global_load_dword v84, v[78:79], off nt
	v_or_b32_e32 v64, 16, v60
	v_or_b32_e32 v66, 18, v60
	v_or_b32_e32 v68, 20, v60
	v_or_b32_e32 v70, 22, v60
	v_or_b32_e32 v72, 24, v60
	v_or_b32_e32 v74, 26, v60
	v_or_b32_e32 v76, 28, v60
	v_or_b32_e32 v78, 30, v60
	v_ashrrev_i32_e32 v65, 31, v64
	v_ashrrev_i32_e32 v67, 31, v66
	v_ashrrev_i32_e32 v69, 31, v68
	v_ashrrev_i32_e32 v71, 31, v70
	v_ashrrev_i32_e32 v73, 31, v72
	v_ashrrev_i32_e32 v75, 31, v74
	v_ashrrev_i32_e32 v77, 31, v76
	v_ashrrev_i32_e32 v79, 31, v78
	v_lshlrev_b64 v[64:65], 14, v[64:65]
	v_lshlrev_b64 v[66:67], 14, v[66:67]
	v_lshlrev_b64 v[68:69], 14, v[68:69]
	v_lshlrev_b64 v[70:71], 14, v[70:71]
	v_lshlrev_b64 v[72:73], 14, v[72:73]
	v_lshlrev_b64 v[74:75], 14, v[74:75]
	v_lshlrev_b64 v[76:77], 14, v[76:77]
	v_lshlrev_b64 v[78:79], 14, v[78:79]
	v_lshl_add_u64 v[64:65], v[62:63], 0, v[64:65]
	v_lshl_add_u64 v[66:67], v[62:63], 0, v[66:67]
	v_lshl_add_u64 v[68:69], v[62:63], 0, v[68:69]
	v_lshl_add_u64 v[70:71], v[62:63], 0, v[70:71]
	v_lshl_add_u64 v[72:73], v[62:63], 0, v[72:73]
	v_lshl_add_u64 v[74:75], v[62:63], 0, v[74:75]
	v_lshl_add_u64 v[76:77], v[62:63], 0, v[76:77]
	v_lshl_add_u64 v[78:79], v[62:63], 0, v[78:79]
	global_load_dword v85, v[64:65], off nt
	global_load_dword v86, v[66:67], off nt
	global_load_dword v87, v[68:69], off nt
	global_load_dword v88, v[70:71], off nt
	global_load_dword v89, v[72:73], off nt
	global_load_dword v90, v[74:75], off nt
	global_load_dword v91, v[76:77], off nt
	global_load_dword v92, v[78:79], off nt
	v_or_b32_e32 v64, 32, v60
	v_or_b32_e32 v66, 34, v60
	v_or_b32_e32 v68, 36, v60
	v_or_b32_e32 v70, 38, v60
	v_or_b32_e32 v72, 40, v60
	v_or_b32_e32 v74, 42, v60
	v_or_b32_e32 v76, 44, v60
	v_or_b32_e32 v78, 46, v60
	v_ashrrev_i32_e32 v65, 31, v64
	v_ashrrev_i32_e32 v67, 31, v66
	v_ashrrev_i32_e32 v69, 31, v68
	v_ashrrev_i32_e32 v71, 31, v70
	v_ashrrev_i32_e32 v73, 31, v72
	v_ashrrev_i32_e32 v75, 31, v74
	v_ashrrev_i32_e32 v77, 31, v76
	v_ashrrev_i32_e32 v79, 31, v78
	v_lshlrev_b64 v[64:65], 14, v[64:65]
	v_lshlrev_b64 v[66:67], 14, v[66:67]
	v_lshlrev_b64 v[68:69], 14, v[68:69]
	v_lshlrev_b64 v[70:71], 14, v[70:71]
	v_lshlrev_b64 v[72:73], 14, v[72:73]
	v_lshlrev_b64 v[74:75], 14, v[74:75]
	v_lshlrev_b64 v[76:77], 14, v[76:77]
	v_lshlrev_b64 v[78:79], 14, v[78:79]
	v_lshl_add_u64 v[64:65], v[62:63], 0, v[64:65]
	v_lshl_add_u64 v[66:67], v[62:63], 0, v[66:67]
	v_lshl_add_u64 v[68:69], v[62:63], 0, v[68:69]
	v_lshl_add_u64 v[70:71], v[62:63], 0, v[70:71]
	v_lshl_add_u64 v[72:73], v[62:63], 0, v[72:73]
	v_lshl_add_u64 v[74:75], v[62:63], 0, v[74:75]
	v_lshl_add_u64 v[76:77], v[62:63], 0, v[76:77]
	v_lshl_add_u64 v[78:79], v[62:63], 0, v[78:79]
	global_load_dword v93, v[64:65], off nt
	global_load_dword v94, v[66:67], off nt
	global_load_dword v95, v[68:69], off nt
	global_load_dword v96, v[70:71], off nt
	global_load_dword v97, v[72:73], off nt
	global_load_dword v98, v[74:75], off nt
	global_load_dword v99, v[76:77], off nt
	s_nop 0
	global_load_dword v78, v[78:79], off nt
	v_or_b32_e32 v64, 48, v60
	v_or_b32_e32 v66, 50, v60
	v_or_b32_e32 v68, 52, v60
	v_or_b32_e32 v70, 54, v60
	v_or_b32_e32 v72, 56, v60
	v_or_b32_e32 v74, 58, v60
	v_or_b32_e32 v76, 60, v60
	v_or_b32_e32 v60, 62, v60
	v_ashrrev_i32_e32 v65, 31, v64
	v_ashrrev_i32_e32 v67, 31, v66
	v_ashrrev_i32_e32 v69, 31, v68
	v_ashrrev_i32_e32 v61, 31, v60
	v_lshlrev_b64 v[64:65], 14, v[64:65]
	v_lshlrev_b64 v[66:67], 14, v[66:67]
	v_lshlrev_b64 v[68:69], 14, v[68:69]
	v_ashrrev_i32_e32 v71, 31, v70
	v_ashrrev_i32_e32 v73, 31, v72
	v_ashrrev_i32_e32 v75, 31, v74
	v_ashrrev_i32_e32 v77, 31, v76
	v_lshlrev_b64 v[60:61], 14, v[60:61]
	v_lshl_add_u64 v[64:65], v[62:63], 0, v[64:65]
	v_lshl_add_u64 v[66:67], v[62:63], 0, v[66:67]
	v_lshl_add_u64 v[68:69], v[62:63], 0, v[68:69]
	v_lshlrev_b64 v[70:71], 14, v[70:71]
	v_lshlrev_b64 v[72:73], 14, v[72:73]
	v_lshlrev_b64 v[74:75], 14, v[74:75]
	v_lshlrev_b64 v[76:77], 14, v[76:77]
	v_lshl_add_u64 v[60:61], v[62:63], 0, v[60:61]
	v_lshl_add_u64 v[70:71], v[62:63], 0, v[70:71]
	v_lshl_add_u64 v[72:73], v[62:63], 0, v[72:73]
	v_lshl_add_u64 v[74:75], v[62:63], 0, v[74:75]
	v_lshl_add_u64 v[76:77], v[62:63], 0, v[76:77]
	global_load_dword v62, v[64:65], off nt
	global_load_dword v63, v[66:67], off nt
	s_nop 0
	global_load_dword v64, v[68:69], off nt
	global_load_dword v65, v[70:71], off nt
	global_load_dword v66, v[72:73], off nt
	global_load_dword v67, v[74:75], off nt
	s_nop 0
	global_load_dword v68, v[76:77], off nt
	s_nop 0
	global_load_dword v60, v[60:61], off nt
	s_waitcnt vmcnt(30)
	ds_write2_b32 v42, v0, v31 offset1:66
	s_waitcnt vmcnt(28)
	ds_write2_b32 v42, v33, v80 offset0:132 offset1:198
	v_add_u32_e32 v0, 0x400, v42
	s_waitcnt vmcnt(26)
	ds_write2_b32 v0, v81, v82 offset0:8 offset1:74
	s_waitcnt vmcnt(24)
	ds_write2_b32 v0, v83, v84 offset0:140 offset1:206
	v_add_u32_e32 v0, 0x800, v42
	s_waitcnt vmcnt(22)
	ds_write2_b32 v0, v85, v86 offset0:16 offset1:82
	s_waitcnt vmcnt(20)
	ds_write2_b32 v0, v87, v88 offset0:148 offset1:214
	v_add_u32_e32 v0, 0xc00, v42
	s_waitcnt vmcnt(18)
	ds_write2_b32 v0, v89, v90 offset0:24 offset1:90
	s_waitcnt vmcnt(16)
	ds_write2_b32 v0, v91, v92 offset0:156 offset1:222
	v_add_u32_e32 v0, 0x1000, v42
	s_waitcnt vmcnt(14)
	ds_write2_b32 v0, v93, v94 offset0:32 offset1:98
	s_waitcnt vmcnt(12)
	ds_write2_b32 v0, v95, v96 offset0:164 offset1:230
	v_add_u32_e32 v0, 0x1400, v42
	s_waitcnt vmcnt(10)
	ds_write2_b32 v0, v97, v98 offset0:40 offset1:106
	s_waitcnt vmcnt(8)
	ds_write2_b32 v0, v99, v78 offset0:172 offset1:238
	v_add_u32_e32 v0, 0x1800, v42
	s_waitcnt vmcnt(6)
	ds_write2_b32 v0, v62, v63 offset0:48 offset1:114
	s_waitcnt vmcnt(4)
	ds_write2_b32 v0, v64, v65 offset0:180 offset1:246
	v_add_u32_e32 v0, 0x1c00, v42
	s_waitcnt vmcnt(2)
	ds_write2_b32 v0, v66, v67 offset0:56 offset1:122
	s_waitcnt vmcnt(0)
	ds_write2_b32 v0, v68, v60 offset0:188 offset1:254
	s_waitcnt lgkmcnt(0)
	ds_read2_b32 v[64:65], v44 offset0:33 offset1:41
	ds_read2_b32 v[66:67], v44 offset1:8
	ds_read2_b32 v[68:69], v44 offset0:66 offset1:74
	ds_read2_b32 v[70:71], v44 offset0:99 offset1:107
	ds_read2_b32 v[72:73], v44 offset0:132 offset1:140
	ds_read2_b32 v[74:75], v44 offset0:165 offset1:173
	ds_read2_b32 v[76:77], v44 offset0:198 offset1:206
	ds_read2_b32 v[78:79], v44 offset0:231 offset1:239
	v_add_u32_e32 v82, v30, v43
	v_ashrrev_i32_e32 v33, 31, v32
	v_ashrrev_i32_e32 v83, 31, v82
	v_lshl_add_u64 v[80:81], v[32:33], 1, v[28:29]
	v_lshlrev_b64 v[30:31], 11, v[82:83]
	s_waitcnt lgkmcnt(6)
	v_cvt_pk_bf16_f32 v60, v66, v64
	s_waitcnt lgkmcnt(4)
	v_cvt_pk_bf16_f32 v61, v68, v70
	s_waitcnt lgkmcnt(2)
	v_cvt_pk_bf16_f32 v62, v72, v74
	s_waitcnt lgkmcnt(0)
	v_cvt_pk_bf16_f32 v63, v76, v78
	v_lshl_add_u64 v[30:31], v[80:81], 0, v[30:31]
	global_store_dwordx4 v[30:31], v[60:63], off
	v_cvt_pk_bf16_f32 v30, v67, v65
	v_cvt_pk_bf16_f32 v31, v69, v71
	v_add_u32_e32 v60, 8, v82
	v_ashrrev_i32_e32 v61, 31, v60
	v_cvt_pk_bf16_f32 v32, v73, v75
	v_cvt_pk_bf16_f32 v33, v77, v79
	v_lshlrev_b64 v[60:61], 11, v[60:61]
	ds_read2_b32 v[62:63], v44 offset0:49 offset1:57
	ds_read2_b32 v[64:65], v44 offset0:16 offset1:24
	ds_read2_b32 v[66:67], v44 offset0:82 offset1:90
	ds_read2_b32 v[68:69], v44 offset0:115 offset1:123
	ds_read2_b32 v[70:71], v44 offset0:148 offset1:156
	ds_read2_b32 v[72:73], v44 offset0:181 offset1:189
	ds_read2_b32 v[74:75], v44 offset0:214 offset1:222
	ds_read2_b32 v[76:77], v44 offset0:247 offset1:255
	v_lshl_add_u64 v[60:61], v[80:81], 0, v[60:61]
	global_store_dwordx4 v[60:61], v[30:33], off
	v_add_u32_e32 v60, 16, v82
	v_ashrrev_i32_e32 v61, 31, v60
	v_lshlrev_b64 v[60:61], 11, v[60:61]
	s_waitcnt lgkmcnt(6)
	v_cvt_pk_bf16_f32 v30, v64, v62
	s_waitcnt lgkmcnt(4)
	v_cvt_pk_bf16_f32 v31, v66, v68
	s_waitcnt lgkmcnt(2)
	v_cvt_pk_bf16_f32 v32, v70, v72
	s_waitcnt lgkmcnt(0)
	v_cvt_pk_bf16_f32 v33, v74, v76
	v_lshl_add_u64 v[60:61], v[80:81], 0, v[60:61]
	global_store_dwordx4 v[60:61], v[30:33], off
	v_add_u32_e32 v60, 24, v82
	v_ashrrev_i32_e32 v61, 31, v60
	v_lshlrev_b64 v[60:61], 11, v[60:61]
	v_cvt_pk_bf16_f32 v30, v65, v63
	v_cvt_pk_bf16_f32 v31, v67, v69
	v_cvt_pk_bf16_f32 v32, v71, v73
	v_cvt_pk_bf16_f32 v33, v75, v77
	v_lshl_add_u64 v[60:61], v[80:81], 0, v[60:61]
	global_store_dwordx4 v[60:61], v[30:33], off
	s_waitcnt lgkmcnt(0)
	s_branch .LBB0_128
